# ss row-scale prefetch via LDS-DMA in all w_in and gate_up GEMM epilogues
# speedup vs baseline: 1.0042x; 1.0042x over previous
; #define PG8_STAGE(bufoff, gbase, voff) do { _Pragma("unroll") for (int _i = 0; _i < 2; ++_i) \
;         __builtin_amdgcn_global_load_lds((const unsigned*)((const char*)(gbase) + (voff)[_i]), (PG8_LAS unsigned*)(lds + (bufoff) + ldsw + _i * 8192), 16, 0, 0); } while (0)
; #define PG8_WAIT_V(n) asm volatile("s_waitcnt vmcnt(" #n ")" ::: "memory")
; #define PG8_BAR __builtin_amdgcn_s_barrier()
; template <class Epi, class Sched, bool ALIGN_EPI = false, bool SP2 = false>
; __device__ __forceinline__ void gemm_phase(PG8_LAS unsigned char* lds, const Gemm g, const Sched& S, const Epi& E, int tid_in) {
;     ...
;     if constexpr (SP2) {
;         PG8_STAGE(PG8_SB(0, 0), cB, voffB); PG8_STAGE(PG8_SB(0, 1), cB + hstep, voffB); PG8_STAGE(PG8_SA(0, 0), cA, voffA); PG8_STAGE(PG8_SA(0, 1), cA + hstep, voffA);
;         if (wr == 1) PG8_BAR;
;         PG8_WAIT_V(2); PG8_BAR;
;         PG8_STAGE(PG8_SB(1, 0), cB + kstep, voffB); PG8_STAGE(PG8_SA(1, 0), cA + kstep, voffA); PG8_STAGE(PG8_SB(1, 1), cB + hstep + kstep, voffB);
;         PG8_WAIT_V(6); PG8_BAR;
;     } else {
;         PG8_STAGE(PG8_SB(0, 0), cB, voffB); PG8_STAGE(PG8_SA(0, 0), cA, voffA); PG8_STAGE(PG8_SB(0, 1), cB + hstep, voffB); PG8_STAGE(PG8_SA(0, 1), cA + hstep, voffA);
;         if (wr == 1) PG8_BAR;
;         PG8_WAIT_V(4); PG8_BAR;
;         PG8_STAGE(PG8_SB(1, 0), cB + kstep, voffB); PG8_STAGE(PG8_SA(1, 0), cA + kstep, voffA); PG8_STAGE(PG8_SB(1, 1), cB + hstep + kstep, voffB);
;         PG8_WAIT_V(6); PG8_BAR;
;     }
.LBB0_114:
	s_and_b32 s47, s4, 3
	s_lshl_b32 s4, s5, 13
	s_lshl_b32 s19, s47, 12
	s_add_u32 s14, s10, 0x8a00000
	s_mov_b64 s[16:17], 0x80
	s_addc_u32 s15, s11, 0
	s_add_i32 m0, s31, 0x18000
	v_lshl_add_u64 v[6:7], v[6:7], 0, s[16:17]
	s_waitcnt vmcnt(2)
	s_barrier
	global_load_lds_dwordx4 v[6:7], off
	v_lshl_add_u64 v[4:5], v[4:5], 0, s[16:17]
	s_add_i32 m0, s31, 0x1a000
	s_add_i32 s48, s31, 0x8000
	s_add_i32 s49, s31, 0xa000
	global_load_lds_dwordx4 v[4:5], off
	v_lshl_add_u64 v[0:1], v[0:1], 0, s[16:17]
	s_mov_b32 m0, s48
	s_add_u32 s22, s26, 0x40080
	global_load_lds_dwordx4 v[0:1], off
	v_lshl_add_u64 v[0:1], v[2:3], 0, s[16:17]
	s_mov_b32 m0, s49
	s_addc_u32 s23, s27, 0
	global_load_lds_dwordx4 v[0:1], off
	s_add_i32 m0, s31, 0x1c000
	v_lshl_add_u64 v[0:1], s[22:23], 0, v[130:131]
	global_load_lds_dwordx4 v[0:1], off
	v_lshl_add_u64 v[0:1], s[22:23], 0, v[134:135]
	s_add_i32 m0, s31, 0x1e000
	v_bfe_u32 v2, v8, 4, 2
	global_load_lds_dwordx4 v[0:1], off
	v_and_b32_e32 v1, 15, v8
	v_lshlrev_b32_e32 v0, 4, v2
	v_lshlrev_b32_e32 v4, 2, v8
	v_lshl_or_b32 v192, s5, 6, v1
	v_lshl_add_u32 v239, v192, 6, v0
	v_add_u32_e32 v239, 0x20080, v239
	v_and_b32_e32 v238, 63, v8
	v_lshlrev_b32_e32 v238, 4, v238
	v_and_b32_e32 v240, 0xffffffc0, v8
	v_lshl_add_u32 v238, v240, 5, v238
	v_lshl_or_b32 v1, v1, 6, v0
	v_and_b32_e32 v4, 32, v4
	v_bitop3_b32 v5, v1, s4, v4 bitop3:0xde
	v_bitop3_b32 v193, v1, s19, v4 bitop3:0xde
	v_mov_b32_e32 v1, v131
	v_lshl_add_u64 v[0:1], s[10:11], 0, v[0:1]
	s_add_u32 s100, s10, 0x8900000
	s_addc_u32 s101, s11, 0
	s_mov_b64 s[4:5], 0x8900000
	v_lshl_add_u64 v[136:137], v[0:1], 0, s[4:5]
	v_lshlrev_b32_e32 v0, 5, v2
	v_mov_b32_e32 v1, v131
	v_lshl_add_u64 v[138:139], s[8:9], 0, v[0:1]
	v_lshlrev_b32_e32 v0, 14, v12
	v_and_b32_e32 v0, 0xffff8000, v0
	v_lshl_add_u32 v0, v13, 11, v0
	v_and_b32_e32 v1, 1, v12
	v_lshl_or_b32 v0, v1, 6, v0
	v_lshl_add_u32 v140, v14, 1, v0
	v_lshlrev_b32_e32 v0, 14, v9
	v_and_b32_e32 v0, 0xffff8000, v0
	s_waitcnt vmcnt(6)
	s_cmpk_lt_u32 s18, 0x100
	v_lshl_add_u32 v0, v10, 11, v0
	v_and_b32_e32 v1, 1, v9
	v_lshlrev_b32_e32 v3, 3, v2
	s_cselect_b64 s[18:19], -1, 0
	v_lshl_or_b32 v0, v1, 6, v0
	s_add_i32 s54, 0, 0x10000
	s_add_i32 s55, 0, 0x14000
	v_or_b32_e32 v194, 16, v192
	v_or_b32_e32 v195, 32, v192
	v_or_b32_e32 v196, 48, v192
	s_ashr_i32 s50, s28, 31
	s_mov_b32 s51, s28
	s_ashr_i32 s52, s2, 31
	v_lshl_or_b32 v197, s47, 6, v3
	v_mov_b32_e32 v141, v131
	v_lshl_add_u32 v142, v11, 1, v0
	v_mov_b32_e32 v143, v131
	v_mov_b64_e32 v[144:145], 0x280
	v_mov_b64_e32 v[146:147], 0x27f
	s_movk_i32 s53, 0x51
	v_add_u32_e32 v198, s54, v193
	v_add_u32_e32 v199, s55, v193
	v_add_u32_e32 v200, 0, v5
	v_mov_b32_e32 v202, 0x358637bd
	s_movk_i32 s56, 0x1400
	v_mov_b32_e32 v203, 0x3e38aa3b
	v_mov_b32_e32 v204, 0x3e000000
	s_barrier
	s_branch .LBB0_117

;     __device__ bool next(int i, Unit& u) const { if (i > 0) return false; const int t = c - first; if (t < 0 || t >= nM * nN) return false; u.pm = t % nM; u.pn = t / nM; return true; }
; template <class Epi, class Sched, bool ALIGN_EPI = false, bool SP2 = false>
; __device__ __forceinline__ void gemm_phase(PG8_LAS unsigned char* lds, const Gemm g, const Sched& S, const Epi& E, int tid_in) {
;     ...
;         const bool has_next = S.next(ui + 1, nxt);
;         const char* nA = has_next ? (const char*)g.A + (size_t)nxt.pm * tstep : cA; const char* nB = has_next ? (const char*)g.Bt + (size_t)nxt.pn * tstep : cB;
;     ...
; #pragma unroll
;         for (int a = 0; a < 2; ++a)
; #pragma unroll
;             for (int b = 0; b < 2; ++b)
; #pragma unroll
;                 for (int m = 0; m < 4; ++m)
; #pragma unroll
;                     for (int n = 0; n < 2; ++n) acc[a][b][m][n] = (f32x4){0.f, 0.f, 0.f, 0.f};
;         cur = nxt; cA = nA; cB = nB; ++ui;
.LBB0_119:
	s_ashr_i32 s11, s10, 31
	s_lshl_b64 s[22:23], s[10:11], 19
	s_add_u32 s22, s6, s22
	s_addc_u32 s23, s7, s23
	s_and_b64 s[24:25], s[4:5], exec
	s_cselect_b32 s11, s23, s35
	s_cselect_b32 s37, s22, s34
	s_ashr_i32 s9, s8, 31
	s_lshl_b64 s[24:25], s[8:9], 19
	s_add_u32 s24, s1, s24
	s_addc_u32 s25, s3, s25
	s_and_b64 s[40:41], s[4:5], exec
	s_cselect_b32 s9, s25, s27
	s_cselect_b32 s39, s24, s26
	s_add_u32 s42, s26, 0x100
	s_addc_u32 s43, s27, 0
	s_add_u32 s26, s34, 0x40080
	v_mov_b32_e32 v0, 0
	s_addc_u32 s27, s35, 0
	s_mov_b32 s57, -2
	v_mov_b32_e32 v1, v0
	v_mov_b32_e32 v2, v0
	v_mov_b32_e32 v3, v0
	v_mov_b32_e32 v4, v0
	v_mov_b32_e32 v5, v0
	v_mov_b32_e32 v6, v0
	v_mov_b32_e32 v7, v0
	v_mov_b32_e32 v16, v0
	v_mov_b32_e32 v17, v0
	v_mov_b32_e32 v18, v0
	v_mov_b32_e32 v19, v0
	v_mov_b32_e32 v20, v0
	v_mov_b32_e32 v21, v0
	v_mov_b32_e32 v22, v0
	v_mov_b32_e32 v23, v0
	v_mov_b32_e32 v32, v0
	v_mov_b32_e32 v33, v0
	v_mov_b32_e32 v34, v0
	v_mov_b32_e32 v35, v0
	v_mov_b32_e32 v36, v0
	v_mov_b32_e32 v37, v0
	v_mov_b32_e32 v38, v0
	v_mov_b32_e32 v39, v0
	v_mov_b32_e32 v48, v0
	v_mov_b32_e32 v49, v0
	v_mov_b32_e32 v50, v0
	v_mov_b32_e32 v51, v0
	v_mov_b32_e32 v52, v0
	v_mov_b32_e32 v53, v0
	v_mov_b32_e32 v54, v0
	v_mov_b32_e32 v55, v0
	v_mov_b32_e32 v8, v0
	v_mov_b32_e32 v9, v0
	v_mov_b32_e32 v10, v0
	v_mov_b32_e32 v11, v0
	v_mov_b32_e32 v12, v0
	v_mov_b32_e32 v13, v0
	v_mov_b32_e32 v14, v0
	v_mov_b32_e32 v15, v0
	v_mov_b32_e32 v24, v0
	v_mov_b32_e32 v25, v0
	v_mov_b32_e32 v26, v0
	v_mov_b32_e32 v27, v0
	v_mov_b32_e32 v28, v0
	v_mov_b32_e32 v29, v0
	v_mov_b32_e32 v30, v0
	v_mov_b32_e32 v31, v0
	v_mov_b32_e32 v40, v0
	v_mov_b32_e32 v41, v0
	v_mov_b32_e32 v42, v0
	v_mov_b32_e32 v43, v0
	v_mov_b32_e32 v44, v0
	v_mov_b32_e32 v45, v0
	v_mov_b32_e32 v46, v0
	v_mov_b32_e32 v47, v0
	v_mov_b32_e32 v56, v0
	v_mov_b32_e32 v57, v0
	v_mov_b32_e32 v58, v0
	v_mov_b32_e32 v59, v0
	v_mov_b32_e32 v60, v0
	v_mov_b32_e32 v61, v0
	v_mov_b32_e32 v62, v0
	v_mov_b32_e32 v63, v0
	v_mov_b32_e32 v64, v0
	v_mov_b32_e32 v65, v0
	v_mov_b32_e32 v66, v0
	v_mov_b32_e32 v67, v0
	v_mov_b32_e32 v68, v0
	v_mov_b32_e32 v69, v0
	v_mov_b32_e32 v70, v0
	v_mov_b32_e32 v71, v0
	v_mov_b32_e32 v80, v0
	v_mov_b32_e32 v81, v0
	v_mov_b32_e32 v82, v0
	v_mov_b32_e32 v83, v0
	v_mov_b32_e32 v84, v0
	v_mov_b32_e32 v85, v0
	v_mov_b32_e32 v86, v0
	v_mov_b32_e32 v87, v0
	v_mov_b32_e32 v96, v0
	v_mov_b32_e32 v97, v0
	v_mov_b32_e32 v98, v0
	v_mov_b32_e32 v99, v0
	v_mov_b32_e32 v100, v0
	v_mov_b32_e32 v101, v0
	v_mov_b32_e32 v102, v0
	v_mov_b32_e32 v103, v0
	v_mov_b32_e32 v112, v0
	v_mov_b32_e32 v113, v0
	v_mov_b32_e32 v114, v0
	v_mov_b32_e32 v115, v0
	v_mov_b32_e32 v116, v0
	v_mov_b32_e32 v117, v0
	v_mov_b32_e32 v118, v0
	v_mov_b32_e32 v119, v0
	v_mov_b32_e32 v72, v0
	v_mov_b32_e32 v73, v0
	v_mov_b32_e32 v74, v0
	v_mov_b32_e32 v75, v0
	v_mov_b32_e32 v76, v0
	v_mov_b32_e32 v77, v0
	v_mov_b32_e32 v78, v0
	v_mov_b32_e32 v79, v0
	v_mov_b32_e32 v88, v0
	v_mov_b32_e32 v89, v0
	v_mov_b32_e32 v90, v0
	v_mov_b32_e32 v91, v0
	v_mov_b32_e32 v92, v0
	v_mov_b32_e32 v93, v0
	v_mov_b32_e32 v94, v0
	v_mov_b32_e32 v95, v0
	v_mov_b32_e32 v104, v0
	v_mov_b32_e32 v105, v0
	v_mov_b32_e32 v106, v0
	v_mov_b32_e32 v107, v0
	v_mov_b32_e32 v108, v0
	v_mov_b32_e32 v109, v0
	v_mov_b32_e32 v110, v0
	v_mov_b32_e32 v111, v0
	v_mov_b32_e32 v120, v0
	v_mov_b32_e32 v121, v0
	v_mov_b32_e32 v122, v0
	v_mov_b32_e32 v123, v0
	v_mov_b32_e32 v124, v0
	v_mov_b32_e32 v125, v0
	v_mov_b32_e32 v126, v0
	v_mov_b32_e32 v127, v0
	v_readlane_b32 s98, v252, 5
	s_nop 1
	s_lshl_b32 s98, s98, 5
	s_add_i32 m0, s98, 0x20080
	s_lshl_b32 s98, s38, 14
	s_add_u32 s98, s100, s98
	s_addc_u32 s99, s101, 0
	global_load_lds_dwordx4 v238, s[98:99]
	global_load_lds_dwordx4 v238, s[98:99] offset:1024

; __device__ __forceinline__ float row_part(const float* ss, int row, int fq) { const f32x4 a = ((const f32x4*)(ss + (size_t)row * 16))[fq]; return (a[0] + a[1]) + (a[2] + a[3]); }
; __device__ __forceinline__ float row_finish(float t) { t += shx(t, 16); t += shx(t, 32); return __builtin_amdgcn_rsqf(t * (1.0f / 1024.0f) + RMS_EPS); }
; __device__ __forceinline__ float sq4(f32x4 v) { return (v[0] * v[0] + v[1] * v[1]) + (v[2] * v[2] + v[3] * v[3]); }
;     __device__ __forceinline__ void operator()(const f32x4 (&acc)[2][2][4][2], const Unit& u, int wr, int wc, int fr, int fq) const {
;         const int g = u.pn * 4 + wc;
;         int mode = 0; const float* w = mqw; float sc = 1.f, nsc = 1.f;
;         if (g >= 36) { mode = 2; w = mqw; nsc = qscale; }
;         else if (diff) { if (g < 12) { mode = 2; w = qw; nsc = qscale; } else if (g < 24) { mode = 2; w = kw; } }
;         else { if (g >= 6 && g < 12) sc = 0.125f; else if (g >= 24) mode = 1; }
;         f32x4 wv[2][2];
; #pragma unroll
;         for (int bj = 0; bj < 2; ++bj)
; #pragma unroll
;             for (int n = 0; n < 2; ++n) wv[bj][n] = *(const f32x4*)(w + 32 * bj + 8 * fq + 4 * n) * nsc;
;         const int lcol = u.pn * 256 + 64 * wc + 8 * fq;
;         float rs[2][4];
; #pragma unroll
;         for (int ai = 0; ai < 2; ++ai)
; #pragma unroll
;             for (int m = 0; m < 4; ++m) rs[ai][m] = row_part(ss, u.pm * BM + ai * HALF + wr * 64 + m * 16 + fr, fq);
; #pragma unroll
;         for (int ai = 0; ai < 2; ++ai)
; #pragma unroll
;             for (int m = 0; m < 4; ++m) rs[ai][m] = row_finish(rs[ai][m]);
; #pragma unroll
;         for (int ai = 0; ai < 2; ++ai)
; #pragma unroll
;             for (int m = 0; m < 4; ++m) {
;                 const int row = u.pm * BM + ai * HALF + wr * 64 + m * 16 + fr;
;                 const float rstd = rs[ai][m];
;                 f32x4 v[2][2];
; #pragma unroll
;                 for (int bj = 0; bj < 2; ++bj)
; #pragma unroll
;                     for (int n = 0; n < 2; ++n) v[bj][n] = acc[ai][bj][m][n] * rstd;
;                 if (mode == 2) {
;                     float q = (sq4(v[0][0]) + sq4(v[0][1])) + (sq4(v[1][0]) + sq4(v[1][1]));
;                     q += shx(q, 16); q += shx(q, 32);
;                     const float r2 = __builtin_amdgcn_rsqf(q * (1.0f / 64.0f) + RMS_EPS);
.LBB0_123:
	s_lshl_b32 s9, s36, 2
	s_or_b32 s11, s9, s47
	s_cmp_gt_i32 s11, 35
	s_cselect_b64 s[34:35], -1, 0
	s_cmp_lt_i32 s11, 36
	s_cselect_b64 s[42:43], -1, 0
	s_add_i32 s11, s11, -12
	s_cmp_lt_u32 s11, -6
	s_cselect_b64 s[40:41], -1, 0
	s_sub_i32 s9, s9, 24
	s_cmp_gt_u32 s9, 11
	s_cselect_b64 s[26:27], -1, 0
	s_lshl_b32 s9, s38, 8
	v_add_u32_e32 v176, s9, v192
	v_ashrrev_i32_e32 v177, 31, v176
	v_or_b32_e32 v158, 16, v176
	v_lshlrev_b64 v[148:149], 6, v[176:177]
	v_ashrrev_i32_e32 v159, 31, v158
	v_lshl_add_u64 v[148:149], v[136:137], 0, v[148:149]
	v_lshlrev_b64 v[158:159], 6, v[158:159]
	global_load_dwordx4 v[150:153], v[138:139], off offset:16
	global_load_dwordx4 v[154:157], v[138:139], off
	global_load_dwordx4 v[168:171], v[138:139], off offset:144
	global_load_dwordx4 v[178:181], v[138:139], off offset:128
	v_lshl_add_u64 v[158:159], v[136:137], 0, v[158:159]
	ds_read_b128 v[182:185], v239
	ds_read_b128 v[186:189], v239 offset:1024
	v_or_b32_e32 v148, 32, v176
	v_ashrrev_i32_e32 v149, 31, v148
	v_or_b32_e32 v158, 48, v176
	v_lshlrev_b64 v[148:149], 6, v[148:149]
	v_ashrrev_i32_e32 v159, 31, v158
	v_lshl_add_u64 v[148:149], v[136:137], 0, v[148:149]
	v_lshlrev_b64 v[158:159], 6, v[158:159]
	v_lshl_add_u64 v[158:159], v[136:137], 0, v[158:159]
	ds_read_b128 v[206:209], v239 offset:2048
	ds_read_b128 v[210:213], v239 offset:3072
	v_add_u32_e32 v174, 0x80, v176
	v_ashrrev_i32_e32 v175, 31, v174
	v_add_u32_e32 v172, 0x90, v176
	v_lshlrev_b64 v[148:149], 6, v[174:175]
	v_ashrrev_i32_e32 v173, 31, v172
	v_lshl_add_u64 v[148:149], v[136:137], 0, v[148:149]
	v_lshlrev_b64 v[158:159], 6, v[172:173]
	v_lshl_add_u64 v[158:159], v[136:137], 0, v[158:159]
	ds_read_b128 v[214:217], v239 offset:8192
	ds_read_b128 v[218:221], v239 offset:9216
	v_add_u32_e32 v166, 0xa0, v176
	v_ashrrev_i32_e32 v167, 31, v166
	v_lshlrev_b64 v[148:149], 6, v[166:167]
	v_lshl_add_u64 v[148:149], v[136:137], 0, v[148:149]
	ds_read_b128 v[222:225], v239 offset:10240
	v_add_u32_e32 v148, 0xb0, v176
	v_ashrrev_i32_e32 v149, 31, v148
	v_lshlrev_b64 v[158:159], 6, v[148:149]
	v_lshl_add_u64 v[158:159], v[136:137], 0, v[158:159]
	ds_read_b128 v[226:229], v239 offset:11264
	v_mov_b32_e32 v149, v201
	v_mov_b32_e32 v158, v201
	v_cndmask_b32_e64 v190, v203, 1.0, s[42:43]
	v_lshlrev_b32_e32 v158, 2, v158
	v_xor_b32_e32 v173, 0x80, v158
	v_lshlrev_b32_e32 v149, 2, v149
	v_xor_b32_e32 v149, 64, v149
	v_mov_b32_e32 v167, v201
	s_mov_b64 s[38:39], -1
	v_lshlrev_b32_e32 v167, 2, v167
	v_xor_b32_e32 v167, 64, v167
	s_and_b64 vcc, exec, s[42:43]
	s_waitcnt vmcnt(0) lgkmcnt(0)
	v_pk_mul_f32 v[158:159], v[190:191], v[152:153] op_sel_hi:[0,1]
	v_pk_mul_f32 v[160:161], v[190:191], v[150:151] op_sel_hi:[0,1]
	v_pk_mul_f32 v[152:153], v[190:191], v[168:169] op_sel_hi:[0,1]
	v_pk_mul_f32 v[150:151], v[190:191], v[170:171] op_sel_hi:[0,1]
	v_mov_b32_e32 v168, v183
	v_mov_b32_e32 v169, v184
	v_mov_b32_e32 v183, v185
	v_pk_add_f32 v[168:169], v[168:169], v[182:183]
	v_add_f32_e32 v170, v186, v187
	v_add_f32_e32 v168, v168, v169
	ds_bpermute_b32 v149, v149, v168
	v_add_f32_e32 v171, v188, v189
	v_add_f32_e32 v169, v170, v171
	ds_bpermute_b32 v167, v167, v169
	v_pk_mul_f32 v[162:163], v[190:191], v[156:157] op_sel_hi:[0,1]
	s_waitcnt lgkmcnt(1)
	v_add_f32_e32 v149, v168, v149
	ds_bpermute_b32 v168, v173, v149
	v_pk_mul_f32 v[156:157], v[190:191], v[178:179] op_sel_hi:[0,1]
	v_add_f32_e32 v179, v212, v213
	s_waitcnt lgkmcnt(1)
	v_add_f32_e32 v212, v169, v167
	v_add_f32_e32 v175, v206, v207
	s_waitcnt lgkmcnt(0)
	v_add_f32_e32 v149, v149, v168
	v_fmamk_f32 v149, v149, 0x3a800000, v202
	v_rsq_f32_e32 v168, v149
	v_mov_b32_e32 v149, v201
	v_add_f32_e32 v177, v208, v209
	v_lshlrev_b32_e32 v149, 2, v149
	v_xor_b32_e32 v149, 0x80, v149
	ds_bpermute_b32 v213, v149, v212
	v_mov_b32_e32 v149, v201
	v_add_f32_e32 v170, v175, v177
	v_lshlrev_b32_e32 v149, 2, v149
	v_xor_b32_e32 v149, 64, v149
	ds_bpermute_b32 v149, v149, v170
	v_mov_b32_e32 v167, v201
	v_mov_b32_e32 v169, v201
	v_add_f32_e32 v178, v210, v211
	v_lshlrev_b32_e32 v169, 2, v169
	v_add_f32_e32 v171, v178, v179
	v_xor_b32_e32 v169, 64, v169
	ds_bpermute_b32 v169, v169, v171
	s_waitcnt lgkmcnt(1)
	v_add_f32_e32 v210, v170, v149
	v_lshlrev_b32_e32 v149, 2, v167
	v_xor_b32_e32 v149, 0x80, v149
	ds_bpermute_b32 v211, v149, v210
	v_mov_b32_e32 v149, v201
	s_waitcnt lgkmcnt(1)
	v_add_f32_e32 v208, v171, v169
	v_lshlrev_b32_e32 v149, 2, v149
	v_xor_b32_e32 v149, 0x80, v149
	ds_bpermute_b32 v209, v149, v208
	v_mov_b32_e32 v149, v201
	v_pk_mul_f32 v[164:165], v[190:191], v[154:155] op_sel_hi:[0,1]
	v_pk_mul_f32 v[154:155], v[190:191], v[180:181] op_sel_hi:[0,1]
	v_add_f32_e32 v180, v214, v215
	v_add_f32_e32 v181, v216, v217
	v_lshlrev_b32_e32 v149, 2, v149
	v_add_f32_e32 v175, v180, v181
	v_xor_b32_e32 v149, 64, v149
	ds_bpermute_b32 v149, v149, v175
	v_mov_b32_e32 v167, v201
	v_mov_b32_e32 v169, v201
	v_add_f32_e32 v182, v218, v219
	v_add_f32_e32 v183, v220, v221
	v_lshlrev_b32_e32 v169, 2, v169
	v_add_f32_e32 v177, v182, v183
	v_xor_b32_e32 v169, 64, v169
	ds_bpermute_b32 v169, v169, v177
	s_waitcnt lgkmcnt(1)
	v_add_f32_e32 v206, v175, v149
	v_lshlrev_b32_e32 v149, 2, v167
	v_xor_b32_e32 v149, 0x80, v149
	ds_bpermute_b32 v207, v149, v206
	v_mov_b32_e32 v149, v201
	s_waitcnt lgkmcnt(1)
	v_add_f32_e32 v177, v177, v169
	v_lshlrev_b32_e32 v149, 2, v149
	v_xor_b32_e32 v149, 0x80, v149
	ds_bpermute_b32 v205, v149, v177
	v_mov_b32_e32 v149, v201
	v_add_f32_e32 v184, v222, v223
	v_add_f32_e32 v185, v224, v225
	v_lshlrev_b32_e32 v149, 2, v149
	v_add_f32_e32 v178, v184, v185
	v_xor_b32_e32 v149, 64, v149
	v_mov_b32_e32 v167, v201
	v_mov_b32_e32 v169, v201
	ds_bpermute_b32 v149, v149, v178
	v_add_f32_e32 v186, v226, v227
	v_add_f32_e32 v187, v228, v229
	v_lshlrev_b32_e32 v169, 2, v169
	v_add_f32_e32 v179, v186, v187
	v_xor_b32_e32 v169, 64, v169
	ds_bpermute_b32 v169, v169, v179
	s_waitcnt lgkmcnt(1)
	v_add_f32_e32 v173, v178, v149
	v_lshlrev_b32_e32 v149, 2, v167
	v_mov_b32_e32 v167, v201
	v_xor_b32_e32 v149, 0x80, v149
	v_lshlrev_b32_e32 v167, 2, v167
	ds_bpermute_b32 v175, v149, v173
	s_waitcnt lgkmcnt(1)
	v_add_f32_e32 v149, v179, v169
	v_xor_b32_e32 v167, 0x80, v167
	ds_bpermute_b32 v167, v167, v149
	v_pk_mul_f32 v[190:191], v[126:127], v[168:169] op_sel_hi:[1,0]
	v_pk_mul_f32 v[184:185], v[124:125], v[168:169] op_sel_hi:[1,0]
	v_pk_mul_f32 v[186:187], v[122:123], v[168:169] op_sel_hi:[1,0]
	v_pk_mul_f32 v[188:189], v[120:121], v[168:169] op_sel_hi:[1,0]
	v_pk_mul_f32 v[180:181], v[118:119], v[168:169] op_sel_hi:[1,0]
	v_pk_mul_f32 v[182:183], v[116:117], v[168:169] op_sel_hi:[1,0]
	v_pk_mul_f32 v[178:179], v[114:115], v[168:169] op_sel_hi:[1,0]
	v_pk_mul_f32 v[170:171], v[112:113], v[168:169] op_sel_hi:[1,0]
	s_cbranch_vccnz .LBB0_125
; __device__ __forceinline__ float sq4(f32x4 v) { return (v[0] * v[0] + v[1] * v[1]) + (v[2] * v[2] + v[3] * v[3]); }
;     __device__ __forceinline__ void operator()(const f32x4 (&acc)[2][2][4][2], const Unit& u, int wr, int wc, int fr, int fq) const {
;     ...
;                 if (mode == 2) {
;                     float q = (sq4(v[0][0]) + sq4(v[0][1])) + (sq4(v[1][0]) + sq4(v[1][1]));
;                     q += shx(q, 16); q += shx(q, 32);
;                     const float r2 = __builtin_amdgcn_rsqf(q * (1.0f / 64.0f) + RMS_EPS);
; #pragma unroll
;                     for (int bj = 0; bj < 2; ++bj)
; #pragma unroll
;                         for (int n = 0; n < 2; ++n) v[bj][n] = v[bj][n] * r2 * wv[bj][n];
	v_mov_b32_e32 v114, v185
	v_mov_b32_e32 v115, v183
	v_mov_b32_e32 v112, v184
	v_mov_b32_e32 v113, v182
	v_pk_mul_f32 v[114:115], v[114:115], v[114:115]
	v_mov_b32_e32 v116, v191
	v_mov_b32_e32 v117, v181
	v_pk_fma_f32 v[112:113], v[112:113], v[112:113], v[114:115]
	v_mov_b32_e32 v114, v190
	v_mov_b32_e32 v115, v180
	v_pk_mul_f32 v[116:117], v[116:117], v[116:117]
	v_mov_b32_e32 v118, v187
	v_pk_fma_f32 v[114:115], v[114:115], v[114:115], v[116:117]
	v_mov_b32_e32 v116, v189
	v_mov_b32_e32 v117, v171
	v_pk_add_f32 v[112:113], v[112:113], v[114:115]
	v_mov_b32_e32 v114, v188
	v_mov_b32_e32 v115, v170
	v_pk_mul_f32 v[116:117], v[116:117], v[116:117]
	v_mov_b32_e32 v119, v179
	v_pk_fma_f32 v[114:115], v[114:115], v[114:115], v[116:117]
	v_mov_b32_e32 v116, v186
	v_mov_b32_e32 v117, v178
	v_pk_mul_f32 v[118:119], v[118:119], v[118:119]
	s_mov_b64 s[38:39], 0
	v_pk_fma_f32 v[116:117], v[116:117], v[116:117], v[118:119]
	s_nop 0
	v_pk_add_f32 v[114:115], v[114:115], v[116:117]
	s_nop 0
	v_pk_add_f32 v[112:113], v[112:113], v[114:115]
	s_nop 0
	v_add_f32_e32 v112, v112, v113
	v_mov_b32_e32 v113, v201
	s_nop 0
	v_lshlrev_b32_e32 v113, 2, v113
	v_xor_b32_e32 v113, 64, v113
	ds_bpermute_b32 v113, v113, v112
	s_waitcnt lgkmcnt(0)
	v_add_f32_e32 v112, v112, v113
	v_mov_b32_e32 v113, v201
	s_nop 0
	v_lshlrev_b32_e32 v113, 2, v113
	v_xor_b32_e32 v113, 0x80, v113
	ds_bpermute_b32 v113, v113, v112
	s_waitcnt lgkmcnt(0)
	v_add_f32_e32 v112, v112, v113
	v_fmamk_f32 v112, v112, 0x3c800000, v202
	v_rsq_f32_e32 v124, v112
	s_nop 0
	v_pk_mul_f32 v[112:113], v[184:185], v[124:125] op_sel_hi:[1,0]
	v_pk_mul_f32 v[114:115], v[190:191], v[124:125] op_sel_hi:[1,0]
	v_pk_mul_f32 v[116:117], v[188:189], v[124:125] op_sel_hi:[1,0]
	v_pk_mul_f32 v[118:119], v[186:187], v[124:125] op_sel_hi:[1,0]
	v_pk_mul_f32 v[120:121], v[182:183], v[124:125] op_sel_hi:[1,0]
	v_pk_mul_f32 v[122:123], v[180:181], v[124:125] op_sel_hi:[1,0]
	v_pk_mul_f32 v[168:169], v[170:171], v[124:125] op_sel_hi:[1,0]
	v_pk_mul_f32 v[124:125], v[178:179], v[124:125] op_sel_hi:[1,0]
	v_pk_mul_f32 v[114:115], v[162:163], v[114:115]
	v_pk_mul_f32 v[112:113], v[164:165], v[112:113]
	v_pk_mul_f32 v[118:119], v[158:159], v[118:119]
	v_pk_mul_f32 v[116:117], v[160:161], v[116:117]
	v_pk_mul_f32 v[122:123], v[154:155], v[122:123]
	v_pk_mul_f32 v[120:121], v[156:157], v[120:121]
	v_pk_mul_f32 v[126:127], v[150:151], v[124:125]
	v_pk_mul_f32 v[124:125], v[152:153], v[168:169]

; #define PG8_STAGE(bufoff, gbase, voff) do { _Pragma("unroll") for (int _i = 0; _i < 2; ++_i) \
;         __builtin_amdgcn_global_load_lds((const unsigned*)((const char*)(gbase) + (voff)[_i]), (PG8_LAS unsigned*)(lds + (bufoff) + ldsw + _i * 8192), 16, 0, 0); } while (0)
; #define PG8_WAIT_V(n) asm volatile("s_waitcnt vmcnt(" #n ")" ::: "memory")
; #define PG8_BAR __builtin_amdgcn_s_barrier()
; template <class Epi, class Sched, bool ALIGN_EPI = false, bool SP2 = false>
; __device__ __forceinline__ void gemm_phase(PG8_LAS unsigned char* lds, const Gemm g, const Sched& S, const Epi& E, int tid_in) {
;     ...
;     if constexpr (SP2) {
;         PG8_STAGE(PG8_SB(0, 0), cB, voffB); PG8_STAGE(PG8_SB(0, 1), cB + hstep, voffB); PG8_STAGE(PG8_SA(0, 0), cA, voffA); PG8_STAGE(PG8_SA(0, 1), cA + hstep, voffA);
;         if (wr == 1) PG8_BAR;
;         PG8_WAIT_V(2); PG8_BAR;
;         PG8_STAGE(PG8_SB(1, 0), cB + kstep, voffB); PG8_STAGE(PG8_SA(1, 0), cA + kstep, voffA); PG8_STAGE(PG8_SB(1, 1), cB + hstep + kstep, voffB);
;         PG8_WAIT_V(6); PG8_BAR;
;     } else {
;         PG8_STAGE(PG8_SB(0, 0), cB, voffB); PG8_STAGE(PG8_SA(0, 0), cA, voffA); PG8_STAGE(PG8_SB(0, 1), cB + hstep, voffB); PG8_STAGE(PG8_SA(0, 1), cA + hstep, voffA);
;         if (wr == 1) PG8_BAR;
;         PG8_WAIT_V(4); PG8_BAR;
;         PG8_STAGE(PG8_SB(1, 0), cB + kstep, voffB); PG8_STAGE(PG8_SA(1, 0), cA + kstep, voffA); PG8_STAGE(PG8_SB(1, 1), cB + hstep + kstep, voffB);
;         PG8_WAIT_V(6); PG8_BAR;
;     }
.LBB0_706:
	s_and_b32 s53, s22, 3
	s_lshl_b32 s14, s27, 13
	s_lshl_b32 s15, s53, 12
	s_add_u32 s22, s10, 0x8a00000
	s_addc_u32 s23, s11, 0
	s_add_u32 s54, s12, 0x100
	s_mov_b64 s[24:25], 0x80
	s_addc_u32 s55, s13, 0
	s_add_i32 m0, s31, 0x18000
	v_lshl_add_u64 v[6:7], v[6:7], 0, s[24:25]
	s_waitcnt vmcnt(2)
	s_barrier
	global_load_lds_dwordx4 v[6:7], off
	v_lshl_add_u64 v[4:5], v[4:5], 0, s[24:25]
	s_add_i32 m0, s31, 0x1a000
	s_add_i32 s56, s31, 0x8000
	s_add_i32 s57, s31, 0xa000
	global_load_lds_dwordx4 v[4:5], off
	v_lshl_add_u64 v[0:1], v[0:1], 0, s[24:25]
	s_mov_b32 m0, s56
	s_add_u32 s12, s48, 0x40080
	global_load_lds_dwordx4 v[0:1], off
	v_lshl_add_u64 v[0:1], v[2:3], 0, s[24:25]
	s_mov_b32 m0, s57
	s_addc_u32 s13, s49, 0
	global_load_lds_dwordx4 v[0:1], off
	s_add_i32 m0, s31, 0x1c000
	v_lshl_add_u64 v[0:1], s[12:13], 0, v[130:131]
	global_load_lds_dwordx4 v[0:1], off
	v_lshl_add_u64 v[0:1], s[12:13], 0, v[134:135]
	s_add_i32 m0, s31, 0x1e000
	v_bfe_u32 v2, v8, 4, 2
	global_load_lds_dwordx4 v[0:1], off
	v_and_b32_e32 v1, 15, v8
	v_lshlrev_b32_e32 v0, 3, v2
	v_lshlrev_b32_e32 v2, 4, v2
	v_lshlrev_b32_e32 v3, 2, v8
	v_lshl_or_b32 v174, s27, 6, v1
	v_lshl_add_u32 v239, v174, 6, v2
	v_add_u32_e32 v239, 0x20080, v239
	v_and_b32_e32 v238, 63, v8
	v_lshlrev_b32_e32 v238, 4, v238
	v_and_b32_e32 v240, 0xffffffc0, v8
	v_lshl_add_u32 v238, v240, 5, v238
	v_lshl_or_b32 v1, v1, 6, v2
	v_and_b32_e32 v3, 32, v3
	v_bitop3_b32 v4, v1, s14, v3 bitop3:0xde
	v_bitop3_b32 v175, v1, s15, v3 bitop3:0xde
	v_mov_b32_e32 v3, v131
	v_lshlrev_b32_e32 v1, 14, v12
	v_lshl_add_u64 v[2:3], s[10:11], 0, v[2:3]
	s_add_u32 s100, s10, 0x8900000
	s_addc_u32 s101, s11, 0
	s_mov_b64 s[10:11], 0x8900000
	v_and_b32_e32 v1, 0xffff8000, v1
	v_lshl_add_u64 v[136:137], v[2:3], 0, s[10:11]
	v_lshl_add_u32 v1, v13, 11, v1
	v_and_b32_e32 v2, 1, v12
	v_lshl_or_b32 v1, v2, 6, v1
	v_lshl_add_u32 v138, v14, 1, v1
	v_lshlrev_b32_e32 v1, 14, v9
	v_and_b32_e32 v1, 0xffff8000, v1
	s_waitcnt vmcnt(6)
	s_cmpk_lt_u32 s26, 0x100
	v_lshl_add_u32 v1, v10, 11, v1
	v_and_b32_e32 v2, 1, v9
	s_cselect_b64 s[26:27], -1, 0
	v_lshl_or_b32 v1, v2, 6, v1
	s_add_i32 s62, 0, 0x10000
	s_add_i32 s63, 0, 0x14000
	v_or_b32_e32 v176, 16, v174
	v_or_b32_e32 v177, 32, v174
	v_or_b32_e32 v178, 48, v174
	s_ashr_i32 s58, s28, 31
	s_mov_b32 s59, s28
	s_ashr_i32 s60, s2, 31
	v_lshl_or_b32 v179, s53, 6, v0
	v_mov_b32_e32 v139, v131
	v_lshl_add_u32 v140, v11, 1, v1
	v_mov_b32_e32 v141, v131
	v_mov_b64_e32 v[142:143], 0x280
	v_mov_b64_e32 v[144:145], 0x27f
	s_movk_i32 s61, 0x51
	v_add_u32_e32 v180, s62, v175
	v_add_u32_e32 v181, s63, v175
	v_add_u32_e32 v182, 0, v4
	v_lshlrev_b32_e32 v183, 2, v0
	v_mov_b32_e32 v184, 0x358637bd
	s_movk_i32 s64, 0x1400
	v_mov_b32_e32 v185, 0x3e38aa3b
	s_barrier
	s_branch .LBB0_709

;     __device__ bool next(int i, Unit& u) const { if (i > 0) return false; const int t = c - first; if (t < 0 || t >= nM * nN) return false; u.pm = t % nM; u.pn = t / nM; return true; }
; template <class Epi, class Sched, bool ALIGN_EPI = false, bool SP2 = false>
; __device__ __forceinline__ void gemm_phase(PG8_LAS unsigned char* lds, const Gemm g, const Sched& S, const Epi& E, int tid_in) {
;     ...
;         const bool has_next = S.next(ui + 1, nxt);
;         const char* nA = has_next ? (const char*)g.A + (size_t)nxt.pm * tstep : cA; const char* nB = has_next ? (const char*)g.Bt + (size_t)nxt.pn * tstep : cB;
;     ...
; #pragma unroll
;         for (int a = 0; a < 2; ++a)
; #pragma unroll
;             for (int b = 0; b < 2; ++b)
; #pragma unroll
;                 for (int m = 0; m < 4; ++m)
; #pragma unroll
;                     for (int n = 0; n < 2; ++n) acc[a][b][m][n] = (f32x4){0.f, 0.f, 0.f, 0.f};
;         cur = nxt; cA = nA; cB = nB; ++ui;
.LBB0_711:
	s_ashr_i32 s37, s36, 31
	s_lshl_b64 s[12:13], s[36:37], 19
	s_add_u32 s38, s4, s12
	s_addc_u32 s39, s5, s13
	s_and_b64 s[12:13], s[10:11], exec
	s_cselect_b32 s37, s39, s51
	s_cselect_b32 s65, s38, s50
	s_ashr_i32 s35, s34, 31
	s_lshl_b64 s[12:13], s[34:35], 19
	s_add_u32 s40, s1, s12
	s_addc_u32 s41, s3, s13
	s_and_b64 s[12:13], s[10:11], exec
	s_cselect_b32 s35, s41, s49
	s_cselect_b32 s66, s40, s48
	s_add_u32 s67, s48, 0x100
	s_addc_u32 s68, s49, 0
	s_add_u32 s12, s50, 0x40080
	v_mov_b32_e32 v0, 0
	s_addc_u32 s13, s51, 0
	s_mov_b32 s69, -2
	v_mov_b32_e32 v1, v0
	v_mov_b32_e32 v2, v0
	v_mov_b32_e32 v3, v0
	v_mov_b32_e32 v4, v0
	v_mov_b32_e32 v5, v0
	v_mov_b32_e32 v6, v0
	v_mov_b32_e32 v7, v0
	v_mov_b32_e32 v16, v0
	v_mov_b32_e32 v17, v0
	v_mov_b32_e32 v18, v0
	v_mov_b32_e32 v19, v0
	v_mov_b32_e32 v20, v0
	v_mov_b32_e32 v21, v0
	v_mov_b32_e32 v22, v0
	v_mov_b32_e32 v23, v0
	v_mov_b32_e32 v32, v0
	v_mov_b32_e32 v33, v0
	v_mov_b32_e32 v34, v0
	v_mov_b32_e32 v35, v0
	v_mov_b32_e32 v36, v0
	v_mov_b32_e32 v37, v0
	v_mov_b32_e32 v38, v0
	v_mov_b32_e32 v39, v0
	v_mov_b32_e32 v48, v0
	v_mov_b32_e32 v49, v0
	v_mov_b32_e32 v50, v0
	v_mov_b32_e32 v51, v0
	v_mov_b32_e32 v52, v0
	v_mov_b32_e32 v53, v0
	v_mov_b32_e32 v54, v0
	v_mov_b32_e32 v55, v0
	v_mov_b32_e32 v8, v0
	v_mov_b32_e32 v9, v0
	v_mov_b32_e32 v10, v0
	v_mov_b32_e32 v11, v0
	v_mov_b32_e32 v12, v0
	v_mov_b32_e32 v13, v0
	v_mov_b32_e32 v14, v0
	v_mov_b32_e32 v15, v0
	v_mov_b32_e32 v24, v0
	v_mov_b32_e32 v25, v0
	v_mov_b32_e32 v26, v0
	v_mov_b32_e32 v27, v0
	v_mov_b32_e32 v28, v0
	v_mov_b32_e32 v29, v0
	v_mov_b32_e32 v30, v0
	v_mov_b32_e32 v31, v0
	v_mov_b32_e32 v40, v0
	v_mov_b32_e32 v41, v0
	v_mov_b32_e32 v42, v0
	v_mov_b32_e32 v43, v0
	v_mov_b32_e32 v44, v0
	v_mov_b32_e32 v45, v0
	v_mov_b32_e32 v46, v0
	v_mov_b32_e32 v47, v0
	v_mov_b32_e32 v56, v0
	v_mov_b32_e32 v57, v0
	v_mov_b32_e32 v58, v0
	v_mov_b32_e32 v59, v0
	v_mov_b32_e32 v60, v0
	v_mov_b32_e32 v61, v0
	v_mov_b32_e32 v62, v0
	v_mov_b32_e32 v63, v0
	v_mov_b32_e32 v64, v0
	v_mov_b32_e32 v65, v0
	v_mov_b32_e32 v66, v0
	v_mov_b32_e32 v67, v0
	v_mov_b32_e32 v68, v0
	v_mov_b32_e32 v69, v0
	v_mov_b32_e32 v70, v0
	v_mov_b32_e32 v71, v0
	v_mov_b32_e32 v80, v0
	v_mov_b32_e32 v81, v0
	v_mov_b32_e32 v82, v0
	v_mov_b32_e32 v83, v0
	v_mov_b32_e32 v84, v0
	v_mov_b32_e32 v85, v0
	v_mov_b32_e32 v86, v0
	v_mov_b32_e32 v87, v0
	v_mov_b32_e32 v96, v0
	v_mov_b32_e32 v97, v0
	v_mov_b32_e32 v98, v0
	v_mov_b32_e32 v99, v0
	v_mov_b32_e32 v100, v0
	v_mov_b32_e32 v101, v0
	v_mov_b32_e32 v102, v0
	v_mov_b32_e32 v103, v0
	v_mov_b32_e32 v112, v0
	v_mov_b32_e32 v113, v0
	v_mov_b32_e32 v114, v0
	v_mov_b32_e32 v115, v0
	v_mov_b32_e32 v116, v0
	v_mov_b32_e32 v117, v0
	v_mov_b32_e32 v118, v0
	v_mov_b32_e32 v119, v0
	v_mov_b32_e32 v72, v0
	v_mov_b32_e32 v73, v0
	v_mov_b32_e32 v74, v0
	v_mov_b32_e32 v75, v0
	v_mov_b32_e32 v76, v0
	v_mov_b32_e32 v77, v0
	v_mov_b32_e32 v78, v0
	v_mov_b32_e32 v79, v0
	v_mov_b32_e32 v88, v0
	v_mov_b32_e32 v89, v0
	v_mov_b32_e32 v90, v0
	v_mov_b32_e32 v91, v0
	v_mov_b32_e32 v92, v0
	v_mov_b32_e32 v93, v0
	v_mov_b32_e32 v94, v0
	v_mov_b32_e32 v95, v0
	v_mov_b32_e32 v104, v0
	v_mov_b32_e32 v105, v0
	v_mov_b32_e32 v106, v0
	v_mov_b32_e32 v107, v0
	v_mov_b32_e32 v108, v0
	v_mov_b32_e32 v109, v0
	v_mov_b32_e32 v110, v0
	v_mov_b32_e32 v111, v0
	v_mov_b32_e32 v120, v0
	v_mov_b32_e32 v121, v0
	v_mov_b32_e32 v122, v0
	v_mov_b32_e32 v123, v0
	v_mov_b32_e32 v124, v0
	v_mov_b32_e32 v125, v0
	v_mov_b32_e32 v126, v0
	v_mov_b32_e32 v127, v0
	v_readlane_b32 s98, v252, 5
	s_nop 1
	s_lshl_b32 s98, s98, 5
	s_add_i32 m0, s98, 0x20080
	s_lshl_b32 s98, s46, 14
	s_add_u32 s98, s100, s98
	s_addc_u32 s99, s101, 0
	global_load_lds_dwordx4 v238, s[98:99]
	global_load_lds_dwordx4 v238, s[98:99] offset:1024

; __device__ __forceinline__ float row_part(const float* ss, int row, int fq) { const f32x4 a = ((const f32x4*)(ss + (size_t)row * 16))[fq]; return (a[0] + a[1]) + (a[2] + a[3]); }
; __device__ __forceinline__ float row_finish(float t) { t += shx(t, 16); t += shx(t, 32); return __builtin_amdgcn_rsqf(t * (1.0f / 1024.0f) + RMS_EPS); }
; __device__ __forceinline__ float sq4(f32x4 v) { return (v[0] * v[0] + v[1] * v[1]) + (v[2] * v[2] + v[3] * v[3]); }
;     __device__ __forceinline__ void operator()(const f32x4 (&acc)[2][2][4][2], const Unit& u, int wr, int wc, int fr, int fq) const {
;         const int g = u.pn * 4 + wc;
;         int mode = 0; const float* w = mqw; float sc = 1.f, nsc = 1.f;
;         if (g >= 36) { mode = 2; w = mqw; nsc = qscale; }
;         else if (diff) { if (g < 12) { mode = 2; w = qw; nsc = qscale; } else if (g < 24) { mode = 2; w = kw; } }
;         else { if (g >= 6 && g < 12) sc = 0.125f; else if (g >= 24) mode = 1; }
;         f32x4 wv[2][2];
; #pragma unroll
;         for (int bj = 0; bj < 2; ++bj)
; #pragma unroll
;             for (int n = 0; n < 2; ++n) wv[bj][n] = *(const f32x4*)(w + 32 * bj + 8 * fq + 4 * n) * nsc;
;         const int lcol = u.pn * 256 + 64 * wc + 8 * fq;
;         float rs[2][4];
; #pragma unroll
;         for (int ai = 0; ai < 2; ++ai)
; #pragma unroll
;             for (int m = 0; m < 4; ++m) rs[ai][m] = row_part(ss, u.pm * BM + ai * HALF + wr * 64 + m * 16 + fr, fq);
; #pragma unroll
;         for (int ai = 0; ai < 2; ++ai)
; #pragma unroll
;             for (int m = 0; m < 4; ++m) rs[ai][m] = row_finish(rs[ai][m]);
; #pragma unroll
;         for (int ai = 0; ai < 2; ++ai)
; #pragma unroll
;             for (int m = 0; m < 4; ++m) {
;                 const int row = u.pm * BM + ai * HALF + wr * 64 + m * 16 + fr;
;                 const float rstd = rs[ai][m];
;                 f32x4 v[2][2];
; #pragma unroll
;                 for (int bj = 0; bj < 2; ++bj)
; #pragma unroll
;                     for (int n = 0; n < 2; ++n) v[bj][n] = acc[ai][bj][m][n] * rstd;
;                 if (mode == 2) {
;                     float q = (sq4(v[0][0]) + sq4(v[0][1])) + (sq4(v[1][0]) + sq4(v[1][1]));
;                     q += shx(q, 16); q += shx(q, 32);
;                     const float r2 = __builtin_amdgcn_rsqf(q * (1.0f / 64.0f) + RMS_EPS);
.LBB0_715:
	s_lshl_b32 s12, s44, 2
	s_or_b32 s13, s12, s53
	s_cmp_lt_u32 s12, 24
	s_cselect_b32 s14, s19, s55
	s_cselect_b32 s15, s18, s54
	s_cmp_lt_i32 s13, 12
	s_cselect_b32 s15, s16, s15
	s_cselect_b32 s14, s17, s14
	s_sub_i32 s37, s12, 36
	s_cmp_lt_u32 s37, 0xffffffe8
	s_cselect_b64 vcc, -1, 0
	s_cmp_gt_i32 s13, 35
	s_cselect_b32 s13, s55, s14
	s_cselect_b32 s12, s54, s15
	s_cmp_lt_u32 s37, -12
	s_cselect_b64 s[48:49], -1, 0
	s_lshl_b32 s35, s46, 8
	v_add_u32_e32 v170, s35, v174
	v_ashrrev_i32_e32 v171, 31, v170
	v_or_b32_e32 v156, 16, v170
	v_lshlrev_b64 v[146:147], 6, v[170:171]
	v_ashrrev_i32_e32 v157, 31, v156
	global_load_dwordx4 v[148:151], v183, s[12:13] offset:16
	global_load_dwordx4 v[152:155], v183, s[12:13]
	global_load_dwordx4 v[186:189], v183, s[12:13] offset:144
	global_load_dwordx4 v[190:193], v183, s[12:13] offset:128
	v_lshl_add_u64 v[146:147], v[136:137], 0, v[146:147]
	v_lshlrev_b64 v[156:157], 6, v[156:157]
	v_lshl_add_u64 v[156:157], v[136:137], 0, v[156:157]
	ds_read_b128 v[194:197], v239
	ds_read_b128 v[202:205], v239 offset:1024
	v_or_b32_e32 v146, 32, v170
	v_ashrrev_i32_e32 v147, 31, v146
	v_or_b32_e32 v156, 48, v170
	v_lshlrev_b64 v[146:147], 6, v[146:147]
	v_ashrrev_i32_e32 v157, 31, v156
	v_lshl_add_u64 v[146:147], v[136:137], 0, v[146:147]
	v_lshlrev_b64 v[156:157], 6, v[156:157]
	v_lshl_add_u64 v[156:157], v[136:137], 0, v[156:157]
	ds_read_b128 v[206:209], v239 offset:2048
	ds_read_b128 v[210:213], v239 offset:3072
	v_add_u32_e32 v168, 0x80, v170
	v_ashrrev_i32_e32 v169, 31, v168
	v_add_u32_e32 v166, 0x90, v170
	v_lshlrev_b64 v[146:147], 6, v[168:169]
	v_ashrrev_i32_e32 v167, 31, v166
	v_add_u32_e32 v164, 0xa0, v170
	v_lshl_add_u64 v[146:147], v[136:137], 0, v[146:147]
	v_lshlrev_b64 v[156:157], 6, v[166:167]
	v_ashrrev_i32_e32 v165, 31, v164
	v_lshl_add_u64 v[156:157], v[136:137], 0, v[156:157]
	ds_read_b128 v[214:217], v239 offset:8192
	ds_read_b128 v[218:221], v239 offset:9216
	v_lshlrev_b64 v[146:147], 6, v[164:165]
	v_lshl_add_u64 v[146:147], v[136:137], 0, v[146:147]
	ds_read_b128 v[222:225], v239 offset:10240
	v_add_u32_e32 v146, 0xb0, v170
	v_ashrrev_i32_e32 v147, 31, v146
	v_lshlrev_b64 v[156:157], 6, v[146:147]
	v_lshl_add_u64 v[156:157], v[136:137], 0, v[156:157]
	ds_read_b128 v[226:229], v239 offset:11264
	v_mov_b32_e32 v147, v201
	v_cndmask_b32_e32 v172, 1.0, v185, vcc
	s_cmp_gt_u32 s37, -13
	v_lshlrev_b32_e32 v147, 2, v147
	v_xor_b32_e32 v147, 64, v147
	s_waitcnt vmcnt(0) lgkmcnt(0)
	v_pk_mul_f32 v[156:157], v[172:173], v[150:151] op_sel_hi:[0,1]
	v_pk_mul_f32 v[160:161], v[172:173], v[154:155] op_sel_hi:[0,1]
	v_pk_mul_f32 v[162:163], v[172:173], v[152:153] op_sel_hi:[0,1]
	v_pk_mul_f32 v[158:159], v[172:173], v[148:149] op_sel_hi:[0,1]
	v_pk_mul_f32 v[152:153], v[172:173], v[192:193] op_sel_hi:[0,1]
	v_pk_mul_f32 v[154:155], v[172:173], v[190:191] op_sel_hi:[0,1]
	v_pk_mul_f32 v[148:149], v[172:173], v[188:189] op_sel_hi:[0,1]
	v_pk_mul_f32 v[150:151], v[172:173], v[186:187] op_sel_hi:[0,1]
	v_mov_b32_e32 v172, v195
	v_mov_b32_e32 v173, v196
	v_mov_b32_e32 v195, v197
	v_pk_add_f32 v[172:173], v[172:173], v[194:195]
	v_add_f32_e32 v165, v202, v203
	v_add_f32_e32 v172, v172, v173
	ds_bpermute_b32 v147, v147, v172
	v_add_f32_e32 v167, v204, v205
	v_add_f32_e32 v169, v206, v207
	v_add_f32_e32 v171, v208, v209
	v_add_f32_e32 v186, v210, v211
	s_waitcnt lgkmcnt(0)
	v_add_f32_e32 v147, v172, v147
	v_mov_b32_e32 v172, v201
	v_add_f32_e32 v187, v212, v213
	v_lshlrev_b32_e32 v172, 2, v172
	v_xor_b32_e32 v172, 0x80, v172
	ds_bpermute_b32 v172, v172, v147
	v_add_f32_e32 v165, v165, v167
	v_add_f32_e32 v167, v169, v171
	v_add_f32_e32 v169, v186, v187
	v_mov_b32_e32 v186, v201
	s_waitcnt lgkmcnt(0)
	v_add_f32_e32 v147, v147, v172
	v_lshlrev_b32_e32 v186, 2, v186
	v_xor_b32_e32 v186, 64, v186
	ds_bpermute_b32 v186, v186, v165
	v_fmamk_f32 v147, v147, 0x3a800000, v184
	v_rsq_f32_e32 v196, v147
	v_mov_b32_e32 v147, v201
	v_add_f32_e32 v192, v222, v223
	v_add_f32_e32 v193, v224, v225
	v_lshlrev_b32_e32 v147, 2, v147
	v_add_f32_e32 v194, v226, v227
	v_add_f32_e32 v195, v228, v229
	v_add_f32_e32 v197, v192, v193
	s_waitcnt lgkmcnt(0)
	v_add_f32_e32 v193, v165, v186
	v_xor_b32_e32 v147, 0x80, v147
	v_add_f32_e32 v195, v194, v195
	ds_bpermute_b32 v194, v147, v193
	v_mov_b32_e32 v147, v201
	v_mov_b32_e32 v165, v201
	v_lshlrev_b32_e32 v147, 2, v147
	v_xor_b32_e32 v147, 64, v147
	ds_bpermute_b32 v147, v147, v167
	v_mov_b32_e32 v172, v201
	v_add_f32_e32 v190, v218, v219
	v_lshlrev_b32_e32 v172, 2, v172
	v_add_f32_e32 v191, v220, v221
	v_xor_b32_e32 v172, 64, v172
	v_add_f32_e32 v173, v190, v191
	ds_bpermute_b32 v172, v172, v169
	s_waitcnt lgkmcnt(1)
	v_add_f32_e32 v191, v167, v147
	v_lshlrev_b32_e32 v147, 2, v165
	v_xor_b32_e32 v147, 0x80, v147
	ds_bpermute_b32 v192, v147, v191
	v_mov_b32_e32 v147, v201
	v_add_f32_e32 v188, v214, v215
	v_add_f32_e32 v189, v216, v217
	v_lshlrev_b32_e32 v147, 2, v147
	v_add_f32_e32 v171, v188, v189
	s_waitcnt lgkmcnt(1)
	v_add_f32_e32 v189, v169, v172
	v_xor_b32_e32 v147, 0x80, v147
	ds_bpermute_b32 v190, v147, v189
	v_mov_b32_e32 v147, v201
	v_mov_b32_e32 v165, v201
	v_lshlrev_b32_e32 v147, 2, v147
	v_xor_b32_e32 v147, 64, v147
	ds_bpermute_b32 v147, v147, v171
	v_mov_b32_e32 v167, v201
	v_pk_mul_f32 v[126:127], v[126:127], v[196:197] op_sel_hi:[1,0]
	v_lshlrev_b32_e32 v167, 2, v167
	v_xor_b32_e32 v167, 64, v167
	ds_bpermute_b32 v167, v167, v173
	s_waitcnt lgkmcnt(1)
	v_add_f32_e32 v187, v171, v147
	v_lshlrev_b32_e32 v147, 2, v165
	v_xor_b32_e32 v147, 0x80, v147
	ds_bpermute_b32 v188, v147, v187
	v_mov_b32_e32 v147, v201
	s_waitcnt lgkmcnt(1)
	v_add_f32_e32 v171, v173, v167
	v_lshlrev_b32_e32 v147, 2, v147
	v_xor_b32_e32 v147, 0x80, v147
	ds_bpermute_b32 v186, v147, v171
	v_mov_b32_e32 v147, v201
	v_mov_b32_e32 v165, v201
	v_lshlrev_b32_e32 v147, 2, v147
	v_xor_b32_e32 v147, 64, v147
	v_mov_b32_e32 v167, v201
	ds_bpermute_b32 v147, v147, v197
	v_pk_mul_f32 v[124:125], v[124:125], v[196:197] op_sel_hi:[1,0]
	v_lshlrev_b32_e32 v167, 2, v167
	v_xor_b32_e32 v167, 64, v167
	ds_bpermute_b32 v172, v167, v195
	s_waitcnt lgkmcnt(1)
	v_add_f32_e32 v167, v197, v147
	v_lshlrev_b32_e32 v147, 2, v165
	v_mov_b32_e32 v165, v201
	v_xor_b32_e32 v147, 0x80, v147
	v_lshlrev_b32_e32 v165, 2, v165
	ds_bpermute_b32 v169, v147, v167
	s_waitcnt lgkmcnt(1)
	v_add_f32_e32 v147, v195, v172
	v_xor_b32_e32 v165, 0x80, v165
	ds_bpermute_b32 v165, v165, v147
	v_pk_mul_f32 v[122:123], v[122:123], v[196:197] op_sel_hi:[1,0]
	v_pk_mul_f32 v[172:173], v[120:121], v[196:197] op_sel_hi:[1,0]
	v_pk_mul_f32 v[118:119], v[118:119], v[196:197] op_sel_hi:[1,0]
	v_pk_mul_f32 v[116:117], v[116:117], v[196:197] op_sel_hi:[1,0]
	v_pk_mul_f32 v[114:115], v[114:115], v[196:197] op_sel_hi:[1,0]
	v_pk_mul_f32 v[120:121], v[112:113], v[196:197] op_sel_hi:[1,0]
	s_cbranch_scc1 .LBB0_717
; __device__ __forceinline__ float sq4(f32x4 v) { return (v[0] * v[0] + v[1] * v[1]) + (v[2] * v[2] + v[3] * v[3]); }
;     __device__ __forceinline__ void operator()(const f32x4 (&acc)[2][2][4][2], const Unit& u, int wr, int wc, int fr, int fq) const {
;     ...
;                 if (mode == 2) {
;                     float q = (sq4(v[0][0]) + sq4(v[0][1])) + (sq4(v[1][0]) + sq4(v[1][1]));
;                     q += shx(q, 16); q += shx(q, 32);
;                     const float r2 = __builtin_amdgcn_rsqf(q * (1.0f / 64.0f) + RMS_EPS);
; #pragma unroll
;                     for (int bj = 0; bj < 2; ++bj)
; #pragma unroll
;                         for (int n = 0; n < 2; ++n) v[bj][n] = v[bj][n] * r2 * wv[bj][n];
	v_mov_b32_e32 v196, v125
	v_mov_b32_e32 v197, v117
	v_mov_b32_e32 v112, v124
	v_mov_b32_e32 v113, v116
	v_pk_mul_f32 v[196:197], v[196:197], v[196:197]
	v_mov_b32_e32 v198, v127
	v_mov_b32_e32 v199, v119
	v_pk_fma_f32 v[112:113], v[112:113], v[112:113], v[196:197]
	v_mov_b32_e32 v196, v126
	v_mov_b32_e32 v197, v118
	v_pk_mul_f32 v[198:199], v[198:199], v[198:199]
	v_mov_b32_e32 v202, v123
	v_pk_fma_f32 v[196:197], v[196:197], v[196:197], v[198:199]
	v_mov_b32_e32 v198, v173
	v_mov_b32_e32 v199, v121
	v_pk_add_f32 v[112:113], v[112:113], v[196:197]
	v_mov_b32_e32 v196, v172
	v_mov_b32_e32 v197, v120
	v_pk_mul_f32 v[198:199], v[198:199], v[198:199]
	v_mov_b32_e32 v203, v115
	v_pk_fma_f32 v[196:197], v[196:197], v[196:197], v[198:199]
	v_mov_b32_e32 v198, v122
	v_mov_b32_e32 v199, v114
	v_pk_mul_f32 v[202:203], v[202:203], v[202:203]
	s_nop 0
	v_pk_fma_f32 v[198:199], v[198:199], v[198:199], v[202:203]
	s_nop 0
	v_pk_add_f32 v[196:197], v[196:197], v[198:199]
	s_nop 0
	v_pk_add_f32 v[112:113], v[112:113], v[196:197]
	s_nop 0
	v_add_f32_e32 v112, v112, v113
	v_mov_b32_e32 v113, v201
	s_nop 0
	v_lshlrev_b32_e32 v113, 2, v113
	v_xor_b32_e32 v113, 64, v113
	ds_bpermute_b32 v113, v113, v112
	s_waitcnt lgkmcnt(0)
	v_add_f32_e32 v112, v112, v113
	v_mov_b32_e32 v113, v201
	s_nop 0
	v_lshlrev_b32_e32 v113, 2, v113
	v_xor_b32_e32 v113, 0x80, v113
	ds_bpermute_b32 v113, v113, v112
	s_waitcnt lgkmcnt(0)
	v_add_f32_e32 v112, v112, v113
	v_fmamk_f32 v112, v112, 0x3c800000, v184
	v_rsq_f32_e32 v112, v112
	s_nop 0
	v_pk_mul_f32 v[124:125], v[124:125], v[112:113] op_sel_hi:[1,0]
	v_pk_mul_f32 v[126:127], v[126:127], v[112:113] op_sel_hi:[1,0]
	v_pk_mul_f32 v[172:173], v[172:173], v[112:113] op_sel_hi:[1,0]
	v_pk_mul_f32 v[122:123], v[122:123], v[112:113] op_sel_hi:[1,0]
	v_pk_mul_f32 v[116:117], v[116:117], v[112:113] op_sel_hi:[1,0]
	v_pk_mul_f32 v[118:119], v[118:119], v[112:113] op_sel_hi:[1,0]
	v_pk_mul_f32 v[120:121], v[120:121], v[112:113] op_sel_hi:[1,0]
	v_pk_mul_f32 v[112:113], v[114:115], v[112:113] op_sel_hi:[1,0]
	v_pk_mul_f32 v[126:127], v[160:161], v[126:127]
	v_pk_mul_f32 v[124:125], v[162:163], v[124:125]
	v_pk_mul_f32 v[122:123], v[156:157], v[122:123]
	v_pk_mul_f32 v[172:173], v[158:159], v[172:173]
	v_pk_mul_f32 v[118:119], v[152:153], v[118:119]
	v_pk_mul_f32 v[116:117], v[154:155], v[116:117]
	v_pk_mul_f32 v[114:115], v[148:149], v[112:113]
	v_pk_mul_f32 v[120:121], v[150:151], v[120:121]

; #define PG8_STAGE(bufoff, gbase, voff) do { _Pragma("unroll") for (int _i = 0; _i < 2; ++_i) \
;         __builtin_amdgcn_global_load_lds((const unsigned*)((const char*)(gbase) + (voff)[_i]), (PG8_LAS unsigned*)(lds + (bufoff) + ldsw + _i * 8192), 16, 0, 0); } while (0)
; #define PG8_WAIT_V(n) asm volatile("s_waitcnt vmcnt(" #n ")" ::: "memory")
; #define PG8_BAR __builtin_amdgcn_s_barrier()
; template <class Epi, class Sched, bool ALIGN_EPI = false, bool SP2 = false>
; __device__ __forceinline__ void gemm_phase(PG8_LAS unsigned char* lds, const Gemm g, const Sched& S, const Epi& E, int tid_in) {
;     ...
;     if constexpr (SP2) {
;         PG8_STAGE(PG8_SB(0, 0), cB, voffB); PG8_STAGE(PG8_SB(0, 1), cB + hstep, voffB); PG8_STAGE(PG8_SA(0, 0), cA, voffA); PG8_STAGE(PG8_SA(0, 1), cA + hstep, voffA);
;         if (wr == 1) PG8_BAR;
;         PG8_WAIT_V(2); PG8_BAR;
;         PG8_STAGE(PG8_SB(1, 0), cB + kstep, voffB); PG8_STAGE(PG8_SA(1, 0), cA + kstep, voffA); PG8_STAGE(PG8_SB(1, 1), cB + hstep + kstep, voffB);
;         PG8_WAIT_V(6); PG8_BAR;
;     } else {
;         PG8_STAGE(PG8_SB(0, 0), cB, voffB); PG8_STAGE(PG8_SA(0, 0), cA, voffA); PG8_STAGE(PG8_SB(0, 1), cB + hstep, voffB); PG8_STAGE(PG8_SA(0, 1), cA + hstep, voffA);
;         if (wr == 1) PG8_BAR;
;         PG8_WAIT_V(4); PG8_BAR;
;         PG8_STAGE(PG8_SB(1, 0), cB + kstep, voffB); PG8_STAGE(PG8_SA(1, 0), cA + kstep, voffA); PG8_STAGE(PG8_SB(1, 1), cB + hstep + kstep, voffB);
;         PG8_WAIT_V(6); PG8_BAR;
;     }
.LBB0_1182:
	s_and_b32 s67, s12, 3
	s_lshl_b32 s4, s13, 13
	s_lshl_b32 s5, s67, 12
	s_add_u32 s18, s26, 0x8a00000
	s_mov_b64 s[20:21], 0x80
	s_addc_u32 s19, s27, 0
	s_add_i32 m0, s62, 0x18000
	v_lshl_add_u64 v[6:7], v[6:7], 0, s[20:21]
	s_waitcnt vmcnt(2)
	s_barrier
	global_load_lds_dwordx4 v[6:7], off
	v_lshl_add_u64 v[4:5], v[4:5], 0, s[20:21]
	s_add_i32 m0, s62, 0x1a000
	s_add_i32 s68, s62, 0x8000
	s_add_i32 s69, s62, 0xa000
	global_load_lds_dwordx4 v[4:5], off
	v_lshl_add_u64 v[0:1], v[0:1], 0, s[20:21]
	s_mov_b32 m0, s68
	s_add_u32 s14, s46, 0x40080
	global_load_lds_dwordx4 v[0:1], off
	v_lshl_add_u64 v[0:1], v[2:3], 0, s[20:21]
	s_mov_b32 m0, s69
	s_addc_u32 s15, s47, 0
	global_load_lds_dwordx4 v[0:1], off
	s_add_i32 m0, s62, 0x1c000
	v_lshl_add_u64 v[0:1], s[14:15], 0, v[130:131]
	global_load_lds_dwordx4 v[0:1], off
	v_lshl_add_u64 v[0:1], s[14:15], 0, v[134:135]
	s_add_i32 m0, s62, 0x1e000
	v_bfe_u32 v2, v8, 4, 2
	global_load_lds_dwordx4 v[0:1], off
	v_and_b32_e32 v1, 15, v8
	v_lshlrev_b32_e32 v0, 4, v2
	v_lshlrev_b32_e32 v4, 2, v8
	v_lshl_or_b32 v192, s13, 6, v1
	v_lshl_add_u32 v239, v192, 6, v0
	v_add_u32_e32 v239, 0x20080, v239
	v_and_b32_e32 v238, 63, v8
	v_lshlrev_b32_e32 v238, 4, v238
	v_and_b32_e32 v240, 0xffffffc0, v8
	v_lshl_add_u32 v238, v240, 5, v238
	v_lshl_or_b32 v1, v1, 6, v0
	v_and_b32_e32 v4, 32, v4
	v_bitop3_b32 v5, v1, s4, v4 bitop3:0xde
	v_bitop3_b32 v193, v1, s5, v4 bitop3:0xde
	v_mov_b32_e32 v1, v131
	v_lshl_add_u64 v[0:1], s[26:27], 0, v[0:1]
	s_add_u32 s100, s26, 0x8900000
	s_addc_u32 s101, s27, 0
	s_mov_b64 s[12:13], 0x8900000
	v_lshl_add_u64 v[136:137], v[0:1], 0, s[12:13]
	v_lshlrev_b32_e32 v0, 5, v2
	v_mov_b32_e32 v1, v131
	v_lshl_add_u64 v[138:139], s[24:25], 0, v[0:1]
	v_lshlrev_b32_e32 v0, 14, v12
	v_and_b32_e32 v0, 0xffff8000, v0
	v_lshl_add_u32 v0, v13, 11, v0
	v_and_b32_e32 v1, 1, v12
	v_lshl_or_b32 v0, v1, 6, v0
	v_lshl_add_u32 v140, v14, 1, v0
	v_lshlrev_b32_e32 v0, 14, v9
	v_and_b32_e32 v0, 0xffff8000, v0
	s_waitcnt vmcnt(6)
	s_cmpk_lt_u32 s0, 0x100
	v_lshl_add_u32 v0, v10, 11, v0
	v_and_b32_e32 v1, 1, v9
	v_lshlrev_b32_e32 v3, 3, v2
	s_cselect_b64 s[22:23], -1, 0
	v_lshl_or_b32 v0, v1, 6, v0
	s_add_i32 s73, 0, 0x10000
	s_add_i32 s40, 0, 0x14000
	v_or_b32_e32 v194, 16, v192
	v_or_b32_e32 v195, 32, v192
	v_or_b32_e32 v196, 48, v192
	s_ashr_i32 s70, s28, 31
	s_mov_b32 s71, s28
	s_ashr_i32 s72, s2, 31
	v_lshl_or_b32 v197, s67, 6, v3
	v_mov_b32_e32 v141, v131
	v_lshl_add_u32 v142, v11, 1, v0
	v_mov_b32_e32 v143, v131
	v_mov_b64_e32 v[144:145], 0x280
	v_mov_b64_e32 v[146:147], 0x27f
	v_add_u32_e32 v198, s73, v193
	v_add_u32_e32 v199, s40, v193
	v_add_u32_e32 v200, 0, v5
	v_mov_b32_e32 v202, 0x358637bd
	s_movk_i32 s12, 0x1400
	v_mov_b32_e32 v203, 0x3e38aa3b
	v_mov_b32_e32 v204, 0x3e000000
	s_barrier
	s_branch .LBB0_1185

;     __device__ bool next(int i, Unit& u) const { if (i > 0) return false; const int t = c - first; if (t < 0 || t >= nM * nN) return false; u.pm = t % nM; u.pn = t / nM; return true; }
; template <class Epi, class Sched, bool ALIGN_EPI = false, bool SP2 = false>
; __device__ __forceinline__ void gemm_phase(PG8_LAS unsigned char* lds, const Gemm g, const Sched& S, const Epi& E, int tid_in) {
;     ...
;         const bool has_next = S.next(ui + 1, nxt);
;         const char* nA = has_next ? (const char*)g.A + (size_t)nxt.pm * tstep : cA; const char* nB = has_next ? (const char*)g.Bt + (size_t)nxt.pn * tstep : cB;
;     ...
; #pragma unroll
;         for (int a = 0; a < 2; ++a)
; #pragma unroll
;             for (int b = 0; b < 2; ++b)
; #pragma unroll
;                 for (int m = 0; m < 4; ++m)
; #pragma unroll
;                     for (int n = 0; n < 2; ++n) acc[a][b][m][n] = (f32x4){0.f, 0.f, 0.f, 0.f};
;         cur = nxt; cA = nA; cB = nB; ++ui;
.LBB0_1187:
	s_ashr_i32 s27, s26, 31
	s_lshl_b64 s[42:43], s[26:27], 19
	s_add_u32 s42, s59, s42
	s_addc_u32 s43, s60, s43
	s_and_b64 s[44:45], s[14:15], exec
	s_cselect_b32 s0, s43, s49
	s_cselect_b32 s13, s42, s48
	s_ashr_i32 s25, s24, 31
	s_lshl_b64 s[44:45], s[24:25], 19
	s_add_u32 s44, s3, s44
	s_addc_u32 s45, s58, s45
	s_and_b64 s[54:55], s[14:15], exec
	s_cselect_b32 s25, s45, s47
	s_cselect_b32 s27, s44, s46
	s_add_u32 s33, s46, 0x100
	s_addc_u32 s51, s47, 0
	s_add_u32 s46, s48, 0x40080
	v_mov_b32_e32 v0, 0
	s_addc_u32 s47, s49, 0
	s_mov_b32 s53, -2
	v_mov_b32_e32 v1, v0
	v_mov_b32_e32 v2, v0
	v_mov_b32_e32 v3, v0
	v_mov_b32_e32 v4, v0
	v_mov_b32_e32 v5, v0
	v_mov_b32_e32 v6, v0
	v_mov_b32_e32 v7, v0
	v_mov_b32_e32 v16, v0
	v_mov_b32_e32 v17, v0
	v_mov_b32_e32 v18, v0
	v_mov_b32_e32 v19, v0
	v_mov_b32_e32 v20, v0
	v_mov_b32_e32 v21, v0
	v_mov_b32_e32 v22, v0
	v_mov_b32_e32 v23, v0
	v_mov_b32_e32 v32, v0
	v_mov_b32_e32 v33, v0
	v_mov_b32_e32 v34, v0
	v_mov_b32_e32 v35, v0
	v_mov_b32_e32 v36, v0
	v_mov_b32_e32 v37, v0
	v_mov_b32_e32 v38, v0
	v_mov_b32_e32 v39, v0
	v_mov_b32_e32 v48, v0
	v_mov_b32_e32 v49, v0
	v_mov_b32_e32 v50, v0
	v_mov_b32_e32 v51, v0
	v_mov_b32_e32 v52, v0
	v_mov_b32_e32 v53, v0
	v_mov_b32_e32 v54, v0
	v_mov_b32_e32 v55, v0
	v_mov_b32_e32 v8, v0
	v_mov_b32_e32 v9, v0
	v_mov_b32_e32 v10, v0
	v_mov_b32_e32 v11, v0
	v_mov_b32_e32 v12, v0
	v_mov_b32_e32 v13, v0
	v_mov_b32_e32 v14, v0
	v_mov_b32_e32 v15, v0
	v_mov_b32_e32 v24, v0
	v_mov_b32_e32 v25, v0
	v_mov_b32_e32 v26, v0
	v_mov_b32_e32 v27, v0
	v_mov_b32_e32 v28, v0
	v_mov_b32_e32 v29, v0
	v_mov_b32_e32 v30, v0
	v_mov_b32_e32 v31, v0
	v_mov_b32_e32 v40, v0
	v_mov_b32_e32 v41, v0
	v_mov_b32_e32 v42, v0
	v_mov_b32_e32 v43, v0
	v_mov_b32_e32 v44, v0
	v_mov_b32_e32 v45, v0
	v_mov_b32_e32 v46, v0
	v_mov_b32_e32 v47, v0
	v_mov_b32_e32 v56, v0
	v_mov_b32_e32 v57, v0
	v_mov_b32_e32 v58, v0
	v_mov_b32_e32 v59, v0
	v_mov_b32_e32 v60, v0
	v_mov_b32_e32 v61, v0
	v_mov_b32_e32 v62, v0
	v_mov_b32_e32 v63, v0
	v_mov_b32_e32 v64, v0
	v_mov_b32_e32 v65, v0
	v_mov_b32_e32 v66, v0
	v_mov_b32_e32 v67, v0
	v_mov_b32_e32 v68, v0
	v_mov_b32_e32 v69, v0
	v_mov_b32_e32 v70, v0
	v_mov_b32_e32 v71, v0
	v_mov_b32_e32 v80, v0
	v_mov_b32_e32 v81, v0
	v_mov_b32_e32 v82, v0
	v_mov_b32_e32 v83, v0
	v_mov_b32_e32 v84, v0
	v_mov_b32_e32 v85, v0
	v_mov_b32_e32 v86, v0
	v_mov_b32_e32 v87, v0
	v_mov_b32_e32 v96, v0
	v_mov_b32_e32 v97, v0
	v_mov_b32_e32 v98, v0
	v_mov_b32_e32 v99, v0
	v_mov_b32_e32 v100, v0
	v_mov_b32_e32 v101, v0
	v_mov_b32_e32 v102, v0
	v_mov_b32_e32 v103, v0
	v_mov_b32_e32 v112, v0
	v_mov_b32_e32 v113, v0
	v_mov_b32_e32 v114, v0
	v_mov_b32_e32 v115, v0
	v_mov_b32_e32 v116, v0
	v_mov_b32_e32 v117, v0
	v_mov_b32_e32 v118, v0
	v_mov_b32_e32 v119, v0
	v_mov_b32_e32 v72, v0
	v_mov_b32_e32 v73, v0
	v_mov_b32_e32 v74, v0
	v_mov_b32_e32 v75, v0
	v_mov_b32_e32 v76, v0
	v_mov_b32_e32 v77, v0
	v_mov_b32_e32 v78, v0
	v_mov_b32_e32 v79, v0
	v_mov_b32_e32 v88, v0
	v_mov_b32_e32 v89, v0
	v_mov_b32_e32 v90, v0
	v_mov_b32_e32 v91, v0
	v_mov_b32_e32 v92, v0
	v_mov_b32_e32 v93, v0
	v_mov_b32_e32 v94, v0
	v_mov_b32_e32 v95, v0
	v_mov_b32_e32 v104, v0
	v_mov_b32_e32 v105, v0
	v_mov_b32_e32 v106, v0
	v_mov_b32_e32 v107, v0
	v_mov_b32_e32 v108, v0
	v_mov_b32_e32 v109, v0
	v_mov_b32_e32 v110, v0
	v_mov_b32_e32 v111, v0
	v_mov_b32_e32 v120, v0
	v_mov_b32_e32 v121, v0
	v_mov_b32_e32 v122, v0
	v_mov_b32_e32 v123, v0
	v_mov_b32_e32 v124, v0
	v_mov_b32_e32 v125, v0
	v_mov_b32_e32 v126, v0
	v_mov_b32_e32 v127, v0
	v_readlane_b32 s98, v252, 5
	s_nop 1
	s_lshl_b32 s98, s98, 5
	s_add_i32 m0, s98, 0x20080
	s_lshl_b32 s98, s52, 14
	s_add_u32 s98, s100, s98
	s_addc_u32 s99, s101, 0
	global_load_lds_dwordx4 v238, s[98:99]
	global_load_lds_dwordx4 v238, s[98:99] offset:1024

; __device__ __forceinline__ float row_part(const float* ss, int row, int fq) { const f32x4 a = ((const f32x4*)(ss + (size_t)row * 16))[fq]; return (a[0] + a[1]) + (a[2] + a[3]); }
; __device__ __forceinline__ float row_finish(float t) { t += shx(t, 16); t += shx(t, 32); return __builtin_amdgcn_rsqf(t * (1.0f / 1024.0f) + RMS_EPS); }
; __device__ __forceinline__ float sq4(f32x4 v) { return (v[0] * v[0] + v[1] * v[1]) + (v[2] * v[2] + v[3] * v[3]); }
;     __device__ __forceinline__ void operator()(const f32x4 (&acc)[2][2][4][2], const Unit& u, int wr, int wc, int fr, int fq) const {
;         const int g = u.pn * 4 + wc;
;         int mode = 0; const float* w = mqw; float sc = 1.f, nsc = 1.f;
;         if (g >= 36) { mode = 2; w = mqw; nsc = qscale; }
;         else if (diff) { if (g < 12) { mode = 2; w = qw; nsc = qscale; } else if (g < 24) { mode = 2; w = kw; } }
;         else { if (g >= 6 && g < 12) sc = 0.125f; else if (g >= 24) mode = 1; }
;         f32x4 wv[2][2];
; #pragma unroll
;         for (int bj = 0; bj < 2; ++bj)
; #pragma unroll
;             for (int n = 0; n < 2; ++n) wv[bj][n] = *(const f32x4*)(w + 32 * bj + 8 * fq + 4 * n) * nsc;
;         const int lcol = u.pn * 256 + 64 * wc + 8 * fq;
;         float rs[2][4];
; #pragma unroll
;         for (int ai = 0; ai < 2; ++ai)
; #pragma unroll
;             for (int m = 0; m < 4; ++m) rs[ai][m] = row_part(ss, u.pm * BM + ai * HALF + wr * 64 + m * 16 + fr, fq);
; #pragma unroll
;         for (int ai = 0; ai < 2; ++ai)
; #pragma unroll
;             for (int m = 0; m < 4; ++m) rs[ai][m] = row_finish(rs[ai][m]);
; #pragma unroll
;         for (int ai = 0; ai < 2; ++ai)
; #pragma unroll
;             for (int m = 0; m < 4; ++m) {
;                 const int row = u.pm * BM + ai * HALF + wr * 64 + m * 16 + fr;
;                 const float rstd = rs[ai][m];
;                 f32x4 v[2][2];
; #pragma unroll
;                 for (int bj = 0; bj < 2; ++bj)
; #pragma unroll
;                     for (int n = 0; n < 2; ++n) v[bj][n] = acc[ai][bj][m][n] * rstd;
;                 if (mode == 2) {
;                     float q = (sq4(v[0][0]) + sq4(v[0][1])) + (sq4(v[1][0]) + sq4(v[1][1]));
;                     q += shx(q, 16); q += shx(q, 32);
;                     const float r2 = __builtin_amdgcn_rsqf(q * (1.0f / 64.0f) + RMS_EPS);
.LBB0_1191:
	global_load_dwordx4 v[148:151], v[138:139], off offset:528
	global_load_dwordx4 v[152:155], v[138:139], off offset:512
	global_load_dwordx4 v[166:169], v[138:139], off offset:656
	global_load_dwordx4 v[170:173], v[138:139], off offset:640
	s_lshl_b32 s0, s50, 2
	s_or_b32 s4, s0, s67
	s_cmp_gt_i32 s4, 35
	s_cselect_b64 s[48:49], -1, 0
	s_cmp_lt_i32 s4, 36
	s_cselect_b64 s[56:57], -1, 0
	s_add_i32 s4, s4, -12
	s_cmp_lt_u32 s4, -6
	s_cselect_b64 s[54:55], -1, 0
	s_sub_i32 s0, s0, 24
	s_cmp_gt_u32 s0, 11
	s_cselect_b64 s[46:47], -1, 0
	s_lshl_b32 s0, s52, 8
	v_add_u32_e32 v176, s0, v192
	v_cndmask_b32_e64 v158, v203, 1.0, s[56:57]
	v_ashrrev_i32_e32 v177, 31, v176
	v_add_u32_e32 v174, 0x80, v176
	v_ashrrev_i32_e32 v175, 31, v174
	s_mov_b64 s[52:53], -1
	s_and_b64 vcc, exec, s[56:57]
	s_waitcnt vmcnt(0)
	v_pk_mul_f32 v[150:151], v[158:159], v[150:151] op_sel_hi:[0,1]
	v_pk_mul_f32 v[160:161], v[158:159], v[152:153] op_sel_hi:[0,1]
	v_pk_mul_f32 v[152:153], v[158:159], v[148:149] op_sel_hi:[0,1]
	v_lshlrev_b64 v[148:149], 6, v[176:177]
	v_lshl_add_u64 v[148:149], v[136:137], 0, v[148:149]
	v_pk_mul_f32 v[156:157], v[158:159], v[154:155] op_sel_hi:[0,1]
	v_pk_mul_f32 v[162:163], v[158:159], v[172:173] op_sel_hi:[0,1]
	v_pk_mul_f32 v[164:165], v[158:159], v[170:171] op_sel_hi:[0,1]
	v_pk_mul_f32 v[154:155], v[158:159], v[168:169] op_sel_hi:[0,1]
	v_pk_mul_f32 v[158:159], v[158:159], v[166:167] op_sel_hi:[0,1]
	ds_read_b128 v[166:169], v239
	v_add_u32_e32 v172, 0x90, v176
	v_ashrrev_i32_e32 v173, 31, v172
	s_waitcnt lgkmcnt(0)
	v_mov_b32_e32 v148, v167
	v_mov_b32_e32 v149, v168
	v_mov_b32_e32 v167, v169
	v_pk_add_f32 v[148:149], v[148:149], v[166:167]
	s_nop 0
	v_add_f32_e32 v177, v148, v149
	v_or_b32_e32 v148, 16, v176
	v_ashrrev_i32_e32 v149, 31, v148
	v_lshlrev_b64 v[148:149], 6, v[148:149]
	v_lshl_add_u64 v[148:149], v[136:137], 0, v[148:149]
	ds_read_b128 v[166:169], v239 offset:1024
	s_waitcnt lgkmcnt(0)
	v_add_f32_e32 v148, v166, v167
	v_add_f32_e32 v149, v168, v169
	v_add_f32_e32 v178, v148, v149
	v_or_b32_e32 v148, 32, v176
	v_ashrrev_i32_e32 v149, 31, v148
	v_lshlrev_b64 v[148:149], 6, v[148:149]
	v_lshl_add_u64 v[148:149], v[136:137], 0, v[148:149]
	ds_read_b128 v[166:169], v239 offset:2048
	s_waitcnt lgkmcnt(0)
	v_add_f32_e32 v148, v166, v167
	v_add_f32_e32 v149, v168, v169
	v_add_f32_e32 v179, v148, v149
	v_or_b32_e32 v148, 48, v176
	v_ashrrev_i32_e32 v149, 31, v148
	v_lshlrev_b64 v[148:149], 6, v[148:149]
	v_lshl_add_u64 v[148:149], v[136:137], 0, v[148:149]
	ds_read_b128 v[166:169], v239 offset:3072
	s_waitcnt lgkmcnt(0)
	v_add_f32_e32 v148, v166, v167
	v_add_f32_e32 v149, v168, v169
	v_add_f32_e32 v180, v148, v149
	v_lshlrev_b64 v[148:149], 6, v[174:175]
	v_lshl_add_u64 v[148:149], v[136:137], 0, v[148:149]
	ds_read_b128 v[166:169], v239 offset:8192
	s_waitcnt lgkmcnt(0)
	v_add_f32_e32 v148, v166, v167
	v_add_f32_e32 v149, v168, v169
	v_add_f32_e32 v175, v148, v149
	v_lshlrev_b64 v[148:149], 6, v[172:173]
	v_lshl_add_u64 v[148:149], v[136:137], 0, v[148:149]
	ds_read_b128 v[166:169], v239 offset:9216
	s_waitcnt lgkmcnt(0)
	v_add_f32_e32 v148, v166, v167
	v_add_u32_e32 v166, 0xa0, v176
	v_add_f32_e32 v149, v168, v169
	v_ashrrev_i32_e32 v167, 31, v166
	v_add_f32_e32 v173, v148, v149
	v_lshlrev_b64 v[148:149], 6, v[166:167]
	v_lshl_add_u64 v[148:149], v[136:137], 0, v[148:149]
	ds_read_b128 v[168:171], v239 offset:10240
	s_waitcnt lgkmcnt(0)
	v_add_f32_e32 v148, v168, v169
	v_add_f32_e32 v149, v170, v171
	v_add_f32_e32 v167, v148, v149
	v_add_u32_e32 v148, 0xb0, v176
	v_ashrrev_i32_e32 v149, 31, v148
	v_lshlrev_b64 v[168:169], 6, v[148:149]
	v_lshl_add_u64 v[168:169], v[136:137], 0, v[168:169]
	ds_read_b128 v[168:171], v239 offset:11264
	s_waitcnt lgkmcnt(0)
	v_add_f32_e32 v149, v168, v169
	v_add_f32_e32 v168, v170, v171
	v_add_f32_e32 v149, v149, v168
	v_mov_b32_e32 v168, v201
	v_mov_b32_e32 v169, v201
	v_lshlrev_b32_e32 v168, 2, v168
	v_xor_b32_e32 v168, 64, v168
	ds_bpermute_b32 v168, v168, v177
	s_waitcnt lgkmcnt(0)
	v_add_f32_e32 v168, v177, v168
	v_lshlrev_b32_e32 v169, 2, v169
	v_xor_b32_e32 v169, 0x80, v169
	ds_bpermute_b32 v169, v169, v168
	s_waitcnt lgkmcnt(0)
	v_add_f32_e32 v168, v168, v169
	v_mov_b32_e32 v169, v201
	v_fmamk_f32 v168, v168, 0x3a800000, v202
	v_lshlrev_b32_e32 v169, 2, v169
	v_xor_b32_e32 v169, 64, v169
	ds_bpermute_b32 v169, v169, v178
	v_rsq_f32_e32 v168, v168
	s_waitcnt lgkmcnt(0)
	v_add_f32_e32 v212, v178, v169
	v_mov_b32_e32 v169, v201
	s_nop 0
	v_lshlrev_b32_e32 v169, 2, v169
	v_xor_b32_e32 v169, 0x80, v169
	ds_bpermute_b32 v213, v169, v212
	v_mov_b32_e32 v169, v201
	s_nop 0
	v_lshlrev_b32_e32 v169, 2, v169
	v_xor_b32_e32 v169, 64, v169
	ds_bpermute_b32 v169, v169, v179
	s_waitcnt lgkmcnt(0)
	v_add_f32_e32 v210, v179, v169
	v_mov_b32_e32 v169, v201
	s_nop 0
	v_lshlrev_b32_e32 v169, 2, v169
	v_xor_b32_e32 v169, 0x80, v169
	ds_bpermute_b32 v211, v169, v210
	v_mov_b32_e32 v169, v201
	s_nop 0
	v_lshlrev_b32_e32 v169, 2, v169
	v_xor_b32_e32 v169, 64, v169
	ds_bpermute_b32 v169, v169, v180
	s_waitcnt lgkmcnt(0)
	v_add_f32_e32 v208, v180, v169
	v_mov_b32_e32 v169, v201
	s_nop 0
	v_lshlrev_b32_e32 v169, 2, v169
	v_xor_b32_e32 v169, 0x80, v169
	ds_bpermute_b32 v209, v169, v208
	v_mov_b32_e32 v169, v201
	s_nop 0
	v_lshlrev_b32_e32 v169, 2, v169
	v_xor_b32_e32 v169, 64, v169
	ds_bpermute_b32 v169, v169, v175
	s_waitcnt lgkmcnt(0)
	v_add_f32_e32 v206, v175, v169
	v_mov_b32_e32 v169, v201
	s_nop 0
	v_lshlrev_b32_e32 v169, 2, v169
	v_xor_b32_e32 v169, 0x80, v169
	ds_bpermute_b32 v207, v169, v206
	v_mov_b32_e32 v169, v201
	s_nop 0
	v_lshlrev_b32_e32 v169, 2, v169
	v_xor_b32_e32 v169, 64, v169
	ds_bpermute_b32 v169, v169, v173
	s_waitcnt lgkmcnt(0)
	v_add_f32_e32 v177, v173, v169
	v_mov_b32_e32 v169, v201
	s_nop 0
	v_lshlrev_b32_e32 v169, 2, v169
	v_xor_b32_e32 v169, 0x80, v169
	ds_bpermute_b32 v205, v169, v177
	v_mov_b32_e32 v169, v201
	s_nop 0
	v_lshlrev_b32_e32 v169, 2, v169
	v_xor_b32_e32 v169, 64, v169
	ds_bpermute_b32 v169, v169, v167
	s_waitcnt lgkmcnt(0)
	v_add_f32_e32 v173, v167, v169
	v_mov_b32_e32 v167, v201
	v_pk_mul_f32 v[188:189], v[126:127], v[168:169] op_sel_hi:[1,0]
	v_lshlrev_b32_e32 v167, 2, v167
	v_xor_b32_e32 v167, 0x80, v167
	ds_bpermute_b32 v175, v167, v173
	v_mov_b32_e32 v167, v201
	v_pk_mul_f32 v[190:191], v[124:125], v[168:169] op_sel_hi:[1,0]
	v_lshlrev_b32_e32 v167, 2, v167
	v_xor_b32_e32 v167, 64, v167
	ds_bpermute_b32 v167, v167, v149
	v_pk_mul_f32 v[184:185], v[122:123], v[168:169] op_sel_hi:[1,0]
	v_pk_mul_f32 v[186:187], v[120:121], v[168:169] op_sel_hi:[1,0]
	v_pk_mul_f32 v[180:181], v[118:119], v[168:169] op_sel_hi:[1,0]
	v_pk_mul_f32 v[182:183], v[116:117], v[168:169] op_sel_hi:[1,0]
	s_waitcnt lgkmcnt(0)
	v_add_f32_e32 v149, v149, v167
	v_mov_b32_e32 v167, v201
	v_pk_mul_f32 v[178:179], v[114:115], v[168:169] op_sel_hi:[1,0]
	v_lshlrev_b32_e32 v167, 2, v167
	v_xor_b32_e32 v167, 0x80, v167
	ds_bpermute_b32 v167, v167, v149
	v_pk_mul_f32 v[170:171], v[112:113], v[168:169] op_sel_hi:[1,0]
	s_cbranch_vccnz .LBB0_1193
; __device__ __forceinline__ float sq4(f32x4 v) { return (v[0] * v[0] + v[1] * v[1]) + (v[2] * v[2] + v[3] * v[3]); }
;     __device__ __forceinline__ void operator()(const f32x4 (&acc)[2][2][4][2], const Unit& u, int wr, int wc, int fr, int fq) const {
;     ...
;                 if (mode == 2) {
;                     float q = (sq4(v[0][0]) + sq4(v[0][1])) + (sq4(v[1][0]) + sq4(v[1][1]));
;                     q += shx(q, 16); q += shx(q, 32);
;                     const float r2 = __builtin_amdgcn_rsqf(q * (1.0f / 64.0f) + RMS_EPS);
; #pragma unroll
;                     for (int bj = 0; bj < 2; ++bj)
; #pragma unroll
;                         for (int n = 0; n < 2; ++n) v[bj][n] = v[bj][n] * r2 * wv[bj][n];
	v_mov_b32_e32 v114, v191
	v_mov_b32_e32 v115, v183
	v_mov_b32_e32 v112, v190
	v_mov_b32_e32 v113, v182
	v_pk_mul_f32 v[114:115], v[114:115], v[114:115]
	v_mov_b32_e32 v116, v189
	v_mov_b32_e32 v117, v181
	v_pk_fma_f32 v[112:113], v[112:113], v[112:113], v[114:115]
	v_mov_b32_e32 v114, v188
	v_mov_b32_e32 v115, v180
	v_pk_mul_f32 v[116:117], v[116:117], v[116:117]
	v_mov_b32_e32 v118, v185
	v_pk_fma_f32 v[114:115], v[114:115], v[114:115], v[116:117]
	v_mov_b32_e32 v116, v187
	v_mov_b32_e32 v117, v171
	v_pk_add_f32 v[112:113], v[112:113], v[114:115]
	v_mov_b32_e32 v114, v186
	v_mov_b32_e32 v115, v170
	v_pk_mul_f32 v[116:117], v[116:117], v[116:117]
	v_mov_b32_e32 v119, v179
	v_pk_fma_f32 v[114:115], v[114:115], v[114:115], v[116:117]
	v_mov_b32_e32 v116, v184
	v_mov_b32_e32 v117, v178
	v_pk_mul_f32 v[118:119], v[118:119], v[118:119]
	s_mov_b64 s[52:53], 0
	v_pk_fma_f32 v[116:117], v[116:117], v[116:117], v[118:119]
	s_nop 0
	v_pk_add_f32 v[114:115], v[114:115], v[116:117]
	s_nop 0
	v_pk_add_f32 v[112:113], v[112:113], v[114:115]
	s_nop 0
	v_add_f32_e32 v112, v112, v113
	v_mov_b32_e32 v113, v201
	s_nop 0
	v_lshlrev_b32_e32 v113, 2, v113
	v_xor_b32_e32 v113, 64, v113
	ds_bpermute_b32 v113, v113, v112
	s_waitcnt lgkmcnt(0)
	v_add_f32_e32 v112, v112, v113
	v_mov_b32_e32 v113, v201
	s_nop 0
	v_lshlrev_b32_e32 v113, 2, v113
	v_xor_b32_e32 v113, 0x80, v113
	ds_bpermute_b32 v113, v113, v112
	s_waitcnt lgkmcnt(0)
	v_add_f32_e32 v112, v112, v113
	v_fmamk_f32 v112, v112, 0x3c800000, v202
	v_rsq_f32_e32 v124, v112
	s_nop 0
	v_pk_mul_f32 v[112:113], v[190:191], v[124:125] op_sel_hi:[1,0]
	v_pk_mul_f32 v[114:115], v[188:189], v[124:125] op_sel_hi:[1,0]
	v_pk_mul_f32 v[116:117], v[186:187], v[124:125] op_sel_hi:[1,0]
	v_pk_mul_f32 v[118:119], v[184:185], v[124:125] op_sel_hi:[1,0]
	v_pk_mul_f32 v[120:121], v[182:183], v[124:125] op_sel_hi:[1,0]
	v_pk_mul_f32 v[122:123], v[180:181], v[124:125] op_sel_hi:[1,0]
	v_pk_mul_f32 v[168:169], v[170:171], v[124:125] op_sel_hi:[1,0]
	v_pk_mul_f32 v[124:125], v[178:179], v[124:125] op_sel_hi:[1,0]
	v_pk_mul_f32 v[114:115], v[156:157], v[114:115]
	v_pk_mul_f32 v[112:113], v[160:161], v[112:113]
	v_pk_mul_f32 v[118:119], v[150:151], v[118:119]
	v_pk_mul_f32 v[116:117], v[152:153], v[116:117]
	v_pk_mul_f32 v[122:123], v[162:163], v[122:123]
	v_pk_mul_f32 v[120:121], v[164:165], v[120:121]
	v_pk_mul_f32 v[126:127], v[154:155], v[124:125]
	v_pk_mul_f32 v[124:125], v[158:159], v[168:169]

; #define PG8_STAGE(bufoff, gbase, voff) do { _Pragma("unroll") for (int _i = 0; _i < 2; ++_i) \
;         __builtin_amdgcn_global_load_lds((const unsigned*)((const char*)(gbase) + (voff)[_i]), (PG8_LAS unsigned*)(lds + (bufoff) + ldsw + _i * 8192), 16, 0, 0); } while (0)
; #define PG8_WAIT_V(n) asm volatile("s_waitcnt vmcnt(" #n ")" ::: "memory")
; #define PG8_BAR __builtin_amdgcn_s_barrier()
; template <class Epi, class Sched, bool ALIGN_EPI = false, bool SP2 = false>
; __device__ __forceinline__ void gemm_phase(PG8_LAS unsigned char* lds, const Gemm g, const Sched& S, const Epi& E, int tid_in) {
;     ...
;     if constexpr (SP2) {
;         PG8_STAGE(PG8_SB(0, 0), cB, voffB); PG8_STAGE(PG8_SB(0, 1), cB + hstep, voffB); PG8_STAGE(PG8_SA(0, 0), cA, voffA); PG8_STAGE(PG8_SA(0, 1), cA + hstep, voffA);
;         if (wr == 1) PG8_BAR;
;         PG8_WAIT_V(2); PG8_BAR;
;         PG8_STAGE(PG8_SB(1, 0), cB + kstep, voffB); PG8_STAGE(PG8_SA(1, 0), cA + kstep, voffA); PG8_STAGE(PG8_SB(1, 1), cB + hstep + kstep, voffB);
;         PG8_WAIT_V(6); PG8_BAR;
;     } else {
;         PG8_STAGE(PG8_SB(0, 0), cB, voffB); PG8_STAGE(PG8_SA(0, 0), cA, voffA); PG8_STAGE(PG8_SB(0, 1), cB + hstep, voffB); PG8_STAGE(PG8_SA(0, 1), cA + hstep, voffA);
;         if (wr == 1) PG8_BAR;
;         PG8_WAIT_V(4); PG8_BAR;
;         PG8_STAGE(PG8_SB(1, 0), cB + kstep, voffB); PG8_STAGE(PG8_SA(1, 0), cA + kstep, voffA); PG8_STAGE(PG8_SB(1, 1), cB + hstep + kstep, voffB);
;         PG8_WAIT_V(6); PG8_BAR;
;     }
.LBB0_1750:
	s_add_u32 s20, s6, 0x8a00000
	s_addc_u32 s21, s7, 0
	s_waitcnt lgkmcnt(0)
	s_add_u32 s54, s16, 0x100
	s_addc_u32 s55, s17, 0
	s_add_u32 s56, s18, 0x100
	s_addc_u32 s57, s19, 0
	s_add_u32 s58, s22, 0x300
	s_mov_b64 s[16:17], 0x80
	s_addc_u32 s59, s23, 0
	s_and_b32 s60, s25, 3
	s_add_i32 m0, s40, 0x18000
	v_lshl_add_u64 v[6:7], v[6:7], 0, s[16:17]
	s_lshl_b32 s4, s26, 13
	s_lshl_b32 s5, s60, 12
	s_waitcnt vmcnt(2)
	s_barrier
	global_load_lds_dwordx4 v[6:7], off
	v_lshl_add_u64 v[4:5], v[4:5], 0, s[16:17]
	s_add_i32 m0, s40, 0x1a000
	s_add_i32 s61, s40, 0x8000
	s_add_i32 s62, s40, 0xa000
	global_load_lds_dwordx4 v[4:5], off
	v_lshl_add_u64 v[0:1], v[0:1], 0, s[16:17]
	s_mov_b32 m0, s61
	s_add_u32 s18, s46, 0x40080
	global_load_lds_dwordx4 v[0:1], off
	v_lshl_add_u64 v[0:1], v[2:3], 0, s[16:17]
	s_mov_b32 m0, s62
	s_addc_u32 s19, s47, 0
	global_load_lds_dwordx4 v[0:1], off
	s_add_i32 m0, s40, 0x1c000
	v_lshl_add_u64 v[0:1], s[18:19], 0, v[130:131]
	global_load_lds_dwordx4 v[0:1], off
	v_lshl_add_u64 v[0:1], s[18:19], 0, v[134:135]
	s_add_i32 m0, s40, 0x1e000
	v_bfe_u32 v2, v8, 4, 2
	global_load_lds_dwordx4 v[0:1], off
	v_and_b32_e32 v1, 15, v8
	v_lshlrev_b32_e32 v0, 3, v2
	v_lshlrev_b32_e32 v2, 4, v2
	v_lshlrev_b32_e32 v3, 2, v8
	v_lshl_or_b32 v174, s26, 6, v1
	v_lshl_add_u32 v239, v174, 6, v2
	v_add_u32_e32 v239, 0x20080, v239
	v_and_b32_e32 v238, 63, v8
	v_lshlrev_b32_e32 v238, 4, v238
	v_and_b32_e32 v240, 0xffffffc0, v8
	v_lshl_add_u32 v238, v240, 5, v238
	v_lshl_or_b32 v1, v1, 6, v2
	v_and_b32_e32 v3, 32, v3
	v_bitop3_b32 v4, v1, s4, v3 bitop3:0xde
	v_bitop3_b32 v175, v1, s5, v3 bitop3:0xde
	v_mov_b32_e32 v3, v131
	v_lshlrev_b32_e32 v1, 14, v12
	v_lshl_add_u64 v[2:3], s[6:7], 0, v[2:3]
	s_add_u32 s100, s6, 0x8900000
	s_addc_u32 s101, s7, 0
	s_mov_b64 s[6:7], 0x8900000
	v_and_b32_e32 v1, 0xffff8000, v1
	v_lshl_add_u64 v[136:137], v[2:3], 0, s[6:7]
	v_lshl_add_u32 v1, v13, 11, v1
	v_and_b32_e32 v2, 1, v12
	v_lshl_or_b32 v1, v2, 6, v1
	v_lshl_add_u32 v138, v14, 1, v1
	v_lshlrev_b32_e32 v1, 14, v9
	v_and_b32_e32 v1, 0xffff8000, v1
	s_waitcnt vmcnt(6)
	s_cmpk_lt_u32 s24, 0x100
	v_lshl_add_u32 v1, v10, 11, v1
	v_and_b32_e32 v2, 1, v9
	s_cselect_b64 s[18:19], -1, 0
	v_lshl_or_b32 v1, v2, 6, v1
	s_add_i32 s66, 0, 0x10000
	s_add_i32 s67, 0, 0x14000
	v_or_b32_e32 v176, 16, v174
	v_or_b32_e32 v177, 32, v174
	v_or_b32_e32 v178, 48, v174
	s_ashr_i32 s63, s28, 31
	s_mov_b32 s64, s28
	s_ashr_i32 s65, s2, 31
	v_lshl_or_b32 v179, s60, 6, v0
	v_mov_b32_e32 v139, v131
	v_lshl_add_u32 v140, v11, 1, v1
	v_mov_b32_e32 v141, v131
	v_mov_b64_e32 v[142:143], 0x280
	v_mov_b64_e32 v[144:145], 0x27f
	v_add_u32_e32 v180, s66, v175
	v_add_u32_e32 v181, s67, v175
	v_add_u32_e32 v182, 0, v4
	v_lshlrev_b32_e32 v183, 2, v0
	v_mov_b32_e32 v184, 0x358637bd
	s_movk_i32 s68, 0x1400
	v_mov_b32_e32 v185, 0x3e38aa3b
	s_barrier
	s_branch .LBB0_1753

;     __device__ bool next(int i, Unit& u) const { if (i > 0) return false; const int t = c - first; if (t < 0 || t >= nM * nN) return false; u.pm = t % nM; u.pn = t / nM; return true; }
; template <class Epi, class Sched, bool ALIGN_EPI = false, bool SP2 = false>
; __device__ __forceinline__ void gemm_phase(PG8_LAS unsigned char* lds, const Gemm g, const Sched& S, const Epi& E, int tid_in) {
;     ...
;         const bool has_next = S.next(ui + 1, nxt);
;         const char* nA = has_next ? (const char*)g.A + (size_t)nxt.pm * tstep : cA; const char* nB = has_next ? (const char*)g.Bt + (size_t)nxt.pn * tstep : cB;
;     ...
; #pragma unroll
;         for (int a = 0; a < 2; ++a)
; #pragma unroll
;             for (int b = 0; b < 2; ++b)
; #pragma unroll
;                 for (int m = 0; m < 4; ++m)
; #pragma unroll
;                     for (int n = 0; n < 2; ++n) acc[a][b][m][n] = (f32x4){0.f, 0.f, 0.f, 0.f};
;         cur = nxt; cA = nA; cB = nB; ++ui;
.LBB0_1755:
	s_ashr_i32 s25, s24, 31
	s_lshl_b64 s[26:27], s[24:25], 19
	s_add_u32 s26, s12, s26
	s_addc_u32 s27, s13, s27
	s_and_b64 s[42:43], s[6:7], exec
	s_cselect_b32 s9, s27, s49
	s_cselect_b32 s25, s26, s48
	s_ashr_i32 s23, s22, 31
	s_lshl_b64 s[42:43], s[22:23], 19
	s_add_u32 s42, s0, s42
	s_addc_u32 s43, s3, s43
	s_and_b64 s[50:51], s[6:7], exec
	s_cselect_b32 s23, s43, s47
	s_cselect_b32 s69, s42, s46
	s_add_u32 s70, s46, 0x100
	s_addc_u32 s71, s47, 0
	s_add_u32 s46, s48, 0x40080
	v_mov_b32_e32 v0, 0
	s_addc_u32 s47, s49, 0
	s_mov_b32 s72, -2
	v_mov_b32_e32 v1, v0
	v_mov_b32_e32 v2, v0
	v_mov_b32_e32 v3, v0
	v_mov_b32_e32 v4, v0
	v_mov_b32_e32 v5, v0
	v_mov_b32_e32 v6, v0
	v_mov_b32_e32 v7, v0
	v_mov_b32_e32 v16, v0
	v_mov_b32_e32 v17, v0
	v_mov_b32_e32 v18, v0
	v_mov_b32_e32 v19, v0
	v_mov_b32_e32 v20, v0
	v_mov_b32_e32 v21, v0
	v_mov_b32_e32 v22, v0
	v_mov_b32_e32 v23, v0
	v_mov_b32_e32 v32, v0
	v_mov_b32_e32 v33, v0
	v_mov_b32_e32 v34, v0
	v_mov_b32_e32 v35, v0
	v_mov_b32_e32 v36, v0
	v_mov_b32_e32 v37, v0
	v_mov_b32_e32 v38, v0
	v_mov_b32_e32 v39, v0
	v_mov_b32_e32 v48, v0
	v_mov_b32_e32 v49, v0
	v_mov_b32_e32 v50, v0
	v_mov_b32_e32 v51, v0
	v_mov_b32_e32 v52, v0
	v_mov_b32_e32 v53, v0
	v_mov_b32_e32 v54, v0
	v_mov_b32_e32 v55, v0
	v_mov_b32_e32 v8, v0
	v_mov_b32_e32 v9, v0
	v_mov_b32_e32 v10, v0
	v_mov_b32_e32 v11, v0
	v_mov_b32_e32 v12, v0
	v_mov_b32_e32 v13, v0
	v_mov_b32_e32 v14, v0
	v_mov_b32_e32 v15, v0
	v_mov_b32_e32 v24, v0
	v_mov_b32_e32 v25, v0
	v_mov_b32_e32 v26, v0
	v_mov_b32_e32 v27, v0
	v_mov_b32_e32 v28, v0
	v_mov_b32_e32 v29, v0
	v_mov_b32_e32 v30, v0
	v_mov_b32_e32 v31, v0
	v_mov_b32_e32 v40, v0
	v_mov_b32_e32 v41, v0
	v_mov_b32_e32 v42, v0
	v_mov_b32_e32 v43, v0
	v_mov_b32_e32 v44, v0
	v_mov_b32_e32 v45, v0
	v_mov_b32_e32 v46, v0
	v_mov_b32_e32 v47, v0
	v_mov_b32_e32 v56, v0
	v_mov_b32_e32 v57, v0
	v_mov_b32_e32 v58, v0
	v_mov_b32_e32 v59, v0
	v_mov_b32_e32 v60, v0
	v_mov_b32_e32 v61, v0
	v_mov_b32_e32 v62, v0
	v_mov_b32_e32 v63, v0
	v_mov_b32_e32 v64, v0
	v_mov_b32_e32 v65, v0
	v_mov_b32_e32 v66, v0
	v_mov_b32_e32 v67, v0
	v_mov_b32_e32 v68, v0
	v_mov_b32_e32 v69, v0
	v_mov_b32_e32 v70, v0
	v_mov_b32_e32 v71, v0
	v_mov_b32_e32 v80, v0
	v_mov_b32_e32 v81, v0
	v_mov_b32_e32 v82, v0
	v_mov_b32_e32 v83, v0
	v_mov_b32_e32 v84, v0
	v_mov_b32_e32 v85, v0
	v_mov_b32_e32 v86, v0
	v_mov_b32_e32 v87, v0
	v_mov_b32_e32 v96, v0
	v_mov_b32_e32 v97, v0
	v_mov_b32_e32 v98, v0
	v_mov_b32_e32 v99, v0
	v_mov_b32_e32 v100, v0
	v_mov_b32_e32 v101, v0
	v_mov_b32_e32 v102, v0
	v_mov_b32_e32 v103, v0
	v_mov_b32_e32 v112, v0
	v_mov_b32_e32 v113, v0
	v_mov_b32_e32 v114, v0
	v_mov_b32_e32 v115, v0
	v_mov_b32_e32 v116, v0
	v_mov_b32_e32 v117, v0
	v_mov_b32_e32 v118, v0
	v_mov_b32_e32 v119, v0
	v_mov_b32_e32 v72, v0
	v_mov_b32_e32 v73, v0
	v_mov_b32_e32 v74, v0
	v_mov_b32_e32 v75, v0
	v_mov_b32_e32 v76, v0
	v_mov_b32_e32 v77, v0
	v_mov_b32_e32 v78, v0
	v_mov_b32_e32 v79, v0
	v_mov_b32_e32 v88, v0
	v_mov_b32_e32 v89, v0
	v_mov_b32_e32 v90, v0
	v_mov_b32_e32 v91, v0
	v_mov_b32_e32 v92, v0
	v_mov_b32_e32 v93, v0
	v_mov_b32_e32 v94, v0
	v_mov_b32_e32 v95, v0
	v_mov_b32_e32 v104, v0
	v_mov_b32_e32 v105, v0
	v_mov_b32_e32 v106, v0
	v_mov_b32_e32 v107, v0
	v_mov_b32_e32 v108, v0
	v_mov_b32_e32 v109, v0
	v_mov_b32_e32 v110, v0
	v_mov_b32_e32 v111, v0
	v_mov_b32_e32 v120, v0
	v_mov_b32_e32 v121, v0
	v_mov_b32_e32 v122, v0
	v_mov_b32_e32 v123, v0
	v_mov_b32_e32 v124, v0
	v_mov_b32_e32 v125, v0
	v_mov_b32_e32 v126, v0
	v_mov_b32_e32 v127, v0
	v_readlane_b32 s98, v252, 5
	s_nop 1
	s_lshl_b32 s98, s98, 5
	s_add_i32 m0, s98, 0x20080
	s_lshl_b32 s98, s44, 14
	s_add_u32 s98, s100, s98
	s_addc_u32 s99, s101, 0
	global_load_lds_dwordx4 v238, s[98:99]
	global_load_lds_dwordx4 v238, s[98:99] offset:1024

; __device__ __forceinline__ float row_part(const float* ss, int row, int fq) { const f32x4 a = ((const f32x4*)(ss + (size_t)row * 16))[fq]; return (a[0] + a[1]) + (a[2] + a[3]); }
; __device__ __forceinline__ float row_finish(float t) { t += shx(t, 16); t += shx(t, 32); return __builtin_amdgcn_rsqf(t * (1.0f / 1024.0f) + RMS_EPS); }
; __device__ __forceinline__ float sq4(f32x4 v) { return (v[0] * v[0] + v[1] * v[1]) + (v[2] * v[2] + v[3] * v[3]); }
;     __device__ __forceinline__ void operator()(const f32x4 (&acc)[2][2][4][2], const Unit& u, int wr, int wc, int fr, int fq) const {
;         const int g = u.pn * 4 + wc;
;         int mode = 0; const float* w = mqw; float sc = 1.f, nsc = 1.f;
;         if (g >= 36) { mode = 2; w = mqw; nsc = qscale; }
;         else if (diff) { if (g < 12) { mode = 2; w = qw; nsc = qscale; } else if (g < 24) { mode = 2; w = kw; } }
;         else { if (g >= 6 && g < 12) sc = 0.125f; else if (g >= 24) mode = 1; }
;         f32x4 wv[2][2];
; #pragma unroll
;         for (int bj = 0; bj < 2; ++bj)
; #pragma unroll
;             for (int n = 0; n < 2; ++n) wv[bj][n] = *(const f32x4*)(w + 32 * bj + 8 * fq + 4 * n) * nsc;
;         const int lcol = u.pn * 256 + 64 * wc + 8 * fq;
;         float rs[2][4];
; #pragma unroll
;         for (int ai = 0; ai < 2; ++ai)
; #pragma unroll
;             for (int m = 0; m < 4; ++m) rs[ai][m] = row_part(ss, u.pm * BM + ai * HALF + wr * 64 + m * 16 + fr, fq);
; #pragma unroll
;         for (int ai = 0; ai < 2; ++ai)
; #pragma unroll
;             for (int m = 0; m < 4; ++m) rs[ai][m] = row_finish(rs[ai][m]);
; #pragma unroll
;         for (int ai = 0; ai < 2; ++ai)
; #pragma unroll
;             for (int m = 0; m < 4; ++m) {
;                 const int row = u.pm * BM + ai * HALF + wr * 64 + m * 16 + fr;
;                 const float rstd = rs[ai][m];
;                 f32x4 v[2][2];
; #pragma unroll
;                 for (int bj = 0; bj < 2; ++bj)
; #pragma unroll
;                     for (int n = 0; n < 2; ++n) v[bj][n] = acc[ai][bj][m][n] * rstd;
;                 if (mode == 2) {
;                     float q = (sq4(v[0][0]) + sq4(v[0][1])) + (sq4(v[1][0]) + sq4(v[1][1]));
;                     q += shx(q, 16); q += shx(q, 32);
;                     const float r2 = __builtin_amdgcn_rsqf(q * (1.0f / 64.0f) + RMS_EPS);
.LBB0_1759:
	s_lshl_b32 s4, s8, 2
	s_or_b32 s5, s4, s60
	s_cmp_lt_u32 s4, 24
	s_cselect_b32 s9, s57, s59
	s_cselect_b32 s23, s56, s58
	s_cmp_lt_i32 s5, 12
	s_cselect_b32 s23, s54, s23
	s_cselect_b32 s9, s55, s9
	s_sub_i32 s4, s4, 36
	s_cmp_lt_u32 s4, 0xffffffe8
	s_cselect_b64 vcc, -1, 0
	s_cmp_gt_i32 s5, 35
	s_cselect_b32 s49, s59, s9
	s_cselect_b32 s48, s58, s23
	global_load_dwordx4 v[148:151], v183, s[48:49] offset:16
	global_load_dwordx4 v[154:157], v183, s[48:49]
	global_load_dwordx4 v[162:165], v183, s[48:49] offset:144
	global_load_dwordx4 v[166:169], v183, s[48:49] offset:128
	s_cmp_lt_u32 s4, -12
	v_cndmask_b32_e32 v170, 1.0, v185, vcc
	s_cselect_b64 s[46:47], -1, 0
	s_lshl_b32 s23, s44, 8
	s_cmp_gt_u32 s4, -13
	s_waitcnt vmcnt(0)
	v_pk_mul_f32 v[146:147], v[170:171], v[150:151] op_sel_hi:[0,1]
	v_pk_mul_f32 v[152:153], v[170:171], v[156:157] op_sel_hi:[0,1]
	v_pk_mul_f32 v[156:157], v[170:171], v[154:155] op_sel_hi:[0,1]
	v_pk_mul_f32 v[148:149], v[170:171], v[148:149] op_sel_hi:[0,1]
	v_pk_mul_f32 v[158:159], v[170:171], v[168:169] op_sel_hi:[0,1]
	v_pk_mul_f32 v[160:161], v[170:171], v[166:167] op_sel_hi:[0,1]
	v_pk_mul_f32 v[150:151], v[170:171], v[164:165] op_sel_hi:[0,1]
	v_pk_mul_f32 v[154:155], v[170:171], v[162:163] op_sel_hi:[0,1]
	v_add_u32_e32 v170, s23, v174
	v_ashrrev_i32_e32 v171, 31, v170
	v_lshlrev_b64 v[162:163], 6, v[170:171]
	v_lshl_add_u64 v[162:163], v[136:137], 0, v[162:163]
	ds_read_b128 v[162:165], v239
	v_add_u32_e32 v168, 0x80, v170
	v_ashrrev_i32_e32 v169, 31, v168
	s_waitcnt lgkmcnt(0)
	v_mov_b32_e32 v166, v163
	v_mov_b32_e32 v167, v164
	v_mov_b32_e32 v163, v165
	v_pk_add_f32 v[162:163], v[166:167], v[162:163]
	v_add_u32_e32 v166, 0x90, v170
	v_add_f32_e32 v171, v162, v163
	v_or_b32_e32 v162, 16, v170
	v_ashrrev_i32_e32 v163, 31, v162
	v_lshlrev_b64 v[162:163], 6, v[162:163]
	v_lshl_add_u64 v[162:163], v[136:137], 0, v[162:163]
	ds_read_b128 v[162:165], v239 offset:1024
	v_ashrrev_i32_e32 v167, 31, v166
	s_waitcnt lgkmcnt(0)
	v_add_f32_e32 v162, v162, v163
	v_add_f32_e32 v163, v164, v165
	v_add_f32_e32 v190, v162, v163
	v_or_b32_e32 v162, 32, v170
	v_ashrrev_i32_e32 v163, 31, v162
	v_lshlrev_b64 v[162:163], 6, v[162:163]
	v_lshl_add_u64 v[162:163], v[136:137], 0, v[162:163]
	ds_read_b128 v[162:165], v239 offset:2048
	s_waitcnt lgkmcnt(0)
	v_add_f32_e32 v162, v162, v163
	v_add_f32_e32 v163, v164, v165
	v_add_f32_e32 v191, v162, v163
	v_or_b32_e32 v162, 48, v170
	v_ashrrev_i32_e32 v163, 31, v162
	v_lshlrev_b64 v[162:163], 6, v[162:163]
	v_lshl_add_u64 v[162:163], v[136:137], 0, v[162:163]
	ds_read_b128 v[162:165], v239 offset:3072
	s_waitcnt lgkmcnt(0)
	v_add_f32_e32 v162, v162, v163
	v_add_f32_e32 v163, v164, v165
	v_add_f32_e32 v195, v162, v163
	v_lshlrev_b64 v[162:163], 6, v[168:169]
	v_lshl_add_u64 v[162:163], v[136:137], 0, v[162:163]
	ds_read_b128 v[162:165], v239 offset:8192
	s_waitcnt lgkmcnt(0)
	v_add_f32_e32 v162, v162, v163
	v_add_f32_e32 v163, v164, v165
	v_add_f32_e32 v169, v162, v163
	v_lshlrev_b64 v[162:163], 6, v[166:167]
	v_lshl_add_u64 v[162:163], v[136:137], 0, v[162:163]
	ds_read_b128 v[162:165], v239 offset:9216
	s_waitcnt lgkmcnt(0)
	v_add_f32_e32 v162, v162, v163
	v_add_f32_e32 v163, v164, v165
	v_add_u32_e32 v164, 0xa0, v170
	v_ashrrev_i32_e32 v165, 31, v164
	v_add_f32_e32 v167, v162, v163
	v_lshlrev_b64 v[162:163], 6, v[164:165]
	v_lshl_add_u64 v[162:163], v[136:137], 0, v[162:163]
	ds_read_b128 v[186:189], v239 offset:10240
	s_waitcnt lgkmcnt(0)
	v_add_f32_e32 v162, v186, v187
	v_add_f32_e32 v163, v188, v189
	v_add_f32_e32 v165, v162, v163
	v_add_u32_e32 v162, 0xb0, v170
	v_ashrrev_i32_e32 v163, 31, v162
	v_lshlrev_b64 v[172:173], 6, v[162:163]
	v_lshl_add_u64 v[172:173], v[136:137], 0, v[172:173]
	ds_read_b128 v[186:189], v239 offset:11264
	s_waitcnt lgkmcnt(0)
	v_add_f32_e32 v163, v186, v187
	v_add_f32_e32 v172, v188, v189
	v_add_f32_e32 v163, v163, v172
	v_mov_b32_e32 v172, v201
	s_nop 0
	v_lshlrev_b32_e32 v172, 2, v172
	v_xor_b32_e32 v172, 64, v172
	ds_bpermute_b32 v172, v172, v171
	s_waitcnt lgkmcnt(0)
	v_add_f32_e32 v171, v171, v172
	v_mov_b32_e32 v172, v201
	s_nop 0
	v_lshlrev_b32_e32 v172, 2, v172
	v_xor_b32_e32 v172, 0x80, v172
	ds_bpermute_b32 v172, v172, v171
	s_waitcnt lgkmcnt(0)
	v_add_f32_e32 v171, v171, v172
	v_fmamk_f32 v171, v171, 0x3a800000, v184
	v_rsq_f32_e32 v196, v171
	v_mov_b32_e32 v171, v201
	v_pk_mul_f32 v[126:127], v[126:127], v[196:197] op_sel_hi:[1,0]
	v_lshlrev_b32_e32 v171, 2, v171
	v_xor_b32_e32 v171, 64, v171
	ds_bpermute_b32 v171, v171, v190
	v_pk_mul_f32 v[124:125], v[124:125], v[196:197] op_sel_hi:[1,0]
	v_pk_mul_f32 v[122:123], v[122:123], v[196:197] op_sel_hi:[1,0]
	v_pk_mul_f32 v[172:173], v[120:121], v[196:197] op_sel_hi:[1,0]
	v_pk_mul_f32 v[118:119], v[118:119], v[196:197] op_sel_hi:[1,0]
	s_waitcnt lgkmcnt(0)
; __device__ __forceinline__ float sq4(f32x4 v) { return (v[0] * v[0] + v[1] * v[1]) + (v[2] * v[2] + v[3] * v[3]); }
; __device__ __forceinline__ float row_finish(float t) { t += shx(t, 16); t += shx(t, 32); return __builtin_amdgcn_rsqf(t * (1.0f / 1024.0f) + RMS_EPS); }
;     __device__ __forceinline__ void operator()(const f32x4 (&acc)[2][2][4][2], const Unit& u, int wr, int wc, int fr, int fq) const {
;     ...
;                 if (mode == 2) {
;                     float q = (sq4(v[0][0]) + sq4(v[0][1])) + (sq4(v[1][0]) + sq4(v[1][1]));
;                     q += shx(q, 16); q += shx(q, 32);
;                     const float r2 = __builtin_amdgcn_rsqf(q * (1.0f / 64.0f) + RMS_EPS);
; #pragma unroll
;                     for (int bj = 0; bj < 2; ++bj)
; #pragma unroll
;                         for (int n = 0; n < 2; ++n) v[bj][n] = v[bj][n] * r2 * wv[bj][n];
	v_add_f32_e32 v193, v190, v171
	v_mov_b32_e32 v171, v201
	v_pk_mul_f32 v[116:117], v[116:117], v[196:197] op_sel_hi:[1,0]
	v_lshlrev_b32_e32 v171, 2, v171
	v_xor_b32_e32 v171, 0x80, v171
	ds_bpermute_b32 v194, v171, v193
	v_mov_b32_e32 v171, v201
	v_pk_mul_f32 v[114:115], v[114:115], v[196:197] op_sel_hi:[1,0]
	v_lshlrev_b32_e32 v171, 2, v171
	v_xor_b32_e32 v171, 64, v171
	ds_bpermute_b32 v171, v171, v191
	v_pk_mul_f32 v[120:121], v[112:113], v[196:197] op_sel_hi:[1,0]
	s_waitcnt lgkmcnt(0)
	v_add_f32_e32 v191, v191, v171
	v_mov_b32_e32 v171, v201
	s_nop 0
	v_lshlrev_b32_e32 v171, 2, v171
	v_xor_b32_e32 v171, 0x80, v171
	ds_bpermute_b32 v192, v171, v191
	v_mov_b32_e32 v171, v201
	s_nop 0
	v_lshlrev_b32_e32 v171, 2, v171
	v_xor_b32_e32 v171, 64, v171
	ds_bpermute_b32 v171, v171, v195
	s_waitcnt lgkmcnt(0)
	v_add_f32_e32 v189, v195, v171
	v_mov_b32_e32 v171, v201
	s_nop 0
	v_lshlrev_b32_e32 v171, 2, v171
	v_xor_b32_e32 v171, 0x80, v171
	ds_bpermute_b32 v190, v171, v189
	v_mov_b32_e32 v171, v201
	s_nop 0
	v_lshlrev_b32_e32 v171, 2, v171
	v_xor_b32_e32 v171, 64, v171
	ds_bpermute_b32 v171, v171, v169
	s_waitcnt lgkmcnt(0)
	v_add_f32_e32 v187, v169, v171
	v_mov_b32_e32 v169, v201
	s_nop 0
	v_lshlrev_b32_e32 v169, 2, v169
	v_xor_b32_e32 v169, 0x80, v169
	ds_bpermute_b32 v188, v169, v187
	v_mov_b32_e32 v169, v201
	s_nop 0
	v_lshlrev_b32_e32 v169, 2, v169
	v_xor_b32_e32 v169, 64, v169
	ds_bpermute_b32 v169, v169, v167
	s_waitcnt lgkmcnt(0)
	v_add_f32_e32 v171, v167, v169
	v_mov_b32_e32 v167, v201
	s_nop 0
	v_lshlrev_b32_e32 v167, 2, v167
	v_xor_b32_e32 v167, 0x80, v167
	ds_bpermute_b32 v186, v167, v171
	v_mov_b32_e32 v167, v201
	s_nop 0
	v_lshlrev_b32_e32 v167, 2, v167
	v_xor_b32_e32 v167, 64, v167
	ds_bpermute_b32 v167, v167, v165
	s_waitcnt lgkmcnt(0)
	v_add_f32_e32 v167, v165, v167
	v_mov_b32_e32 v165, v201
	s_nop 0
	v_lshlrev_b32_e32 v165, 2, v165
	v_xor_b32_e32 v165, 0x80, v165
	ds_bpermute_b32 v169, v165, v167
	v_mov_b32_e32 v165, v201
	s_nop 0
	v_lshlrev_b32_e32 v165, 2, v165
	v_xor_b32_e32 v165, 64, v165
	ds_bpermute_b32 v165, v165, v163
	s_waitcnt lgkmcnt(0)
	v_add_f32_e32 v163, v163, v165
	v_mov_b32_e32 v165, v201
	s_nop 0
	v_lshlrev_b32_e32 v165, 2, v165
	v_xor_b32_e32 v165, 0x80, v165
	ds_bpermute_b32 v165, v165, v163
	s_cbranch_scc1 .LBB0_1761
	v_mov_b32_e32 v196, v125
	v_mov_b32_e32 v197, v117
	v_mov_b32_e32 v112, v124
	v_mov_b32_e32 v113, v116
	v_pk_mul_f32 v[196:197], v[196:197], v[196:197]
	v_mov_b32_e32 v198, v127
	v_mov_b32_e32 v199, v119
	v_pk_fma_f32 v[112:113], v[112:113], v[112:113], v[196:197]
	v_mov_b32_e32 v196, v126
	v_mov_b32_e32 v197, v118
	v_pk_mul_f32 v[198:199], v[198:199], v[198:199]
	v_mov_b32_e32 v202, v123
	v_pk_fma_f32 v[196:197], v[196:197], v[196:197], v[198:199]
	v_mov_b32_e32 v198, v173
	v_mov_b32_e32 v199, v121
	v_pk_add_f32 v[112:113], v[112:113], v[196:197]
	v_mov_b32_e32 v196, v172
	v_mov_b32_e32 v197, v120
	v_pk_mul_f32 v[198:199], v[198:199], v[198:199]
	v_mov_b32_e32 v203, v115
	v_pk_fma_f32 v[196:197], v[196:197], v[196:197], v[198:199]
	v_mov_b32_e32 v198, v122
	v_mov_b32_e32 v199, v114
	v_pk_mul_f32 v[202:203], v[202:203], v[202:203]
	s_nop 0
	v_pk_fma_f32 v[198:199], v[198:199], v[198:199], v[202:203]
	s_nop 0
	v_pk_add_f32 v[196:197], v[196:197], v[198:199]
	s_nop 0
	v_pk_add_f32 v[112:113], v[112:113], v[196:197]
	s_nop 0
	v_add_f32_e32 v112, v112, v113
	v_mov_b32_e32 v113, v201
	s_nop 0
	v_lshlrev_b32_e32 v113, 2, v113
	v_xor_b32_e32 v113, 64, v113
	ds_bpermute_b32 v113, v113, v112
	s_waitcnt lgkmcnt(0)
	v_add_f32_e32 v112, v112, v113
	v_mov_b32_e32 v113, v201
	s_nop 0
	v_lshlrev_b32_e32 v113, 2, v113
	v_xor_b32_e32 v113, 0x80, v113
	ds_bpermute_b32 v113, v113, v112
	s_waitcnt lgkmcnt(0)
	v_add_f32_e32 v112, v112, v113
	v_fmamk_f32 v112, v112, 0x3c800000, v184
	v_rsq_f32_e32 v112, v112
	s_nop 0
	v_pk_mul_f32 v[124:125], v[124:125], v[112:113] op_sel_hi:[1,0]
	v_pk_mul_f32 v[126:127], v[126:127], v[112:113] op_sel_hi:[1,0]
	v_pk_mul_f32 v[172:173], v[172:173], v[112:113] op_sel_hi:[1,0]
	v_pk_mul_f32 v[122:123], v[122:123], v[112:113] op_sel_hi:[1,0]
	v_pk_mul_f32 v[116:117], v[116:117], v[112:113] op_sel_hi:[1,0]
	v_pk_mul_f32 v[118:119], v[118:119], v[112:113] op_sel_hi:[1,0]
	v_pk_mul_f32 v[120:121], v[120:121], v[112:113] op_sel_hi:[1,0]
	v_pk_mul_f32 v[112:113], v[114:115], v[112:113] op_sel_hi:[1,0]
	v_pk_mul_f32 v[126:127], v[152:153], v[126:127]
	v_pk_mul_f32 v[124:125], v[156:157], v[124:125]
	v_pk_mul_f32 v[122:123], v[146:147], v[122:123]
	v_pk_mul_f32 v[172:173], v[148:149], v[172:173]
	v_pk_mul_f32 v[118:119], v[158:159], v[118:119]
	v_pk_mul_f32 v[116:117], v[160:161], v[116:117]
	v_pk_mul_f32 v[114:115], v[150:151], v[112:113]
	v_pk_mul_f32 v[120:121], v[154:155], v[120:121]
